# v20 + counted vmcnt ladder on the latent-DFT item first merge-gate load cluster (2 copies)
# speedup vs baseline: 1.0684x; 1.0024x over previous
.LBB0_847:
	v_add_u32_e32 v0, v228, v238
	v_add_u32_e32 v172, v236, v237
	ds_read_b128 v[138:141], v0 offset:32768
	ds_read_b128 v[146:149], v0 offset:34816
	ds_read_b128 v[142:145], v240
	ds_read_b128 v[152:155], v241
	ds_read_b128 v[156:159], v242
	ds_read_b128 v[160:163], v172
	ds_read_b128 v[164:167], v0 offset:36864
	ds_read_b128 v[168:171], v0 offset:38912
	s_add_i32 s6, s6, 1
	s_cmp_lg_u32 s6, 64
	s_waitcnt lgkmcnt(5)
	v_mfma_f32_16x16x32_bf16 v[126:129], v[138:141], v[142:145], v[126:129]
	v_mfma_f32_16x16x32_bf16 v[122:125], v[146:149], v[142:145], v[122:125]
	s_waitcnt lgkmcnt(4)
	v_mfma_f32_16x16x32_bf16 v[110:113], v[138:141], v[152:155], v[110:113]
	v_mfma_f32_16x16x32_bf16 v[106:109], v[146:149], v[152:155], v[106:109]
	s_waitcnt lgkmcnt(1)
	v_mfma_f32_16x16x32_bf16 v[118:121], v[164:167], v[142:145], v[118:121]
	v_mfma_f32_16x16x32_bf16 v[102:105], v[164:167], v[152:155], v[102:105]
	v_mfma_f32_16x16x32_bf16 v[94:97], v[138:141], v[156:159], v[94:97]
	v_mfma_f32_16x16x32_bf16 v[90:93], v[146:149], v[156:159], v[90:93]
	s_waitcnt lgkmcnt(0)
	v_mfma_f32_16x16x32_bf16 v[114:117], v[168:171], v[142:145], v[114:117]
	v_mfma_f32_16x16x32_bf16 v[98:101], v[168:171], v[152:155], v[98:101]
	v_mfma_f32_16x16x32_bf16 v[86:89], v[164:167], v[156:159], v[86:89]
	v_mfma_f32_16x16x32_bf16 v[82:85], v[168:171], v[156:159], v[82:85]
	v_mfma_f32_16x16x32_bf16 v[78:81], v[138:141], v[160:163], v[78:81]
	v_mfma_f32_16x16x32_bf16 v[74:77], v[146:149], v[160:163], v[74:77]
	v_mfma_f32_16x16x32_bf16 v[70:73], v[164:167], v[160:163], v[70:73]
	v_mfma_f32_16x16x32_bf16 v[66:69], v[168:171], v[160:163], v[66:69]
	ds_read_b128 v[138:141], v0 offset:33792
	ds_read_b128 v[142:145], v0 offset:35840
	ds_read_b128 v[152:155], v0 offset:39936
	ds_read_b128 v[156:159], v0 offset:37888
	ds_read_b128 v[146:149], v240 offset:1024
	ds_read_b128 v[160:163], v241 offset:1024
	s_waitcnt lgkmcnt(1)
	v_mfma_f32_16x16x32_bf16 v[126:129], v[138:141], v[146:149], v[126:129]
	v_mfma_f32_16x16x32_bf16 v[122:125], v[142:145], v[146:149], v[122:125]
	v_mfma_f32_16x16x32_bf16 v[118:121], v[156:159], v[146:149], v[118:121]
	v_mfma_f32_16x16x32_bf16 v[114:117], v[152:155], v[146:149], v[114:117]
	ds_read_b128 v[146:149], v242 offset:1024
	s_waitcnt lgkmcnt(1)
	v_mfma_f32_16x16x32_bf16 v[110:113], v[138:141], v[160:163], v[110:113]
	v_mfma_f32_16x16x32_bf16 v[106:109], v[142:145], v[160:163], v[106:109]
	v_mfma_f32_16x16x32_bf16 v[102:105], v[156:159], v[160:163], v[102:105]
	v_mfma_f32_16x16x32_bf16 v[98:101], v[152:155], v[160:163], v[98:101]
	ds_read_b128 v[160:163], v172 offset:1024
	s_waitcnt lgkmcnt(1)
	v_mfma_f32_16x16x32_bf16 v[94:97], v[138:141], v[146:149], v[94:97]
	v_mfma_f32_16x16x32_bf16 v[90:93], v[142:145], v[146:149], v[90:93]
	v_mfma_f32_16x16x32_bf16 v[86:89], v[156:159], v[146:149], v[86:89]
	v_mfma_f32_16x16x32_bf16 v[82:85], v[152:155], v[146:149], v[82:85]
	s_waitcnt lgkmcnt(0)
	v_mfma_f32_16x16x32_bf16 v[78:81], v[138:141], v[160:163], v[78:81]
	v_mfma_f32_16x16x32_bf16 v[74:77], v[142:145], v[160:163], v[74:77]
	v_mfma_f32_16x16x32_bf16 v[70:73], v[156:159], v[160:163], v[70:73]
	v_mfma_f32_16x16x32_bf16 v[66:69], v[152:155], v[160:163], v[66:69]
	s_cbranch_scc1 .LBB0_860
	s_cmp_eq_u32 s22, 0
	s_cbranch_scc1 .LBB0_858
	v_mov_b32_e32 v0, v196
	v_mov_b64_e32 v[152:153], s[30:31]
	v_and_b32_e32 v247, 15, v0
	v_ashrrev_i32_e32 v248, 7, v0
	v_lshl_or_b32 v148, v248, 6, v247
	v_ashrrev_i32_e32 v149, 31, v148
	v_and_b32_e32 v138, 64, v0
	v_lshrrev_b32_e32 v0, 2, v0
	v_lshl_add_u64 v[170:171], s[42:43], 0, v[148:149]
	v_and_or_b32 v0, v0, 12, v138
	v_mad_u64_u32 v[138:139], s[6:7], v170, s90, v[152:153]
	v_mov_b32_e32 v140, v139
	v_mad_u64_u32 v[140:141], s[6:7], v171, s90, v[140:141]
	v_mov_b32_e32 v139, v140
	s_lshl_b64 s[6:7], s[46:47], 1
	v_lshl_add_u64 v[138:139], v[138:139], 0, s[6:7]
	v_lshlrev_b32_e32 v154, 1, v0
	v_mov_b32_e32 v155, v1
	v_lshl_add_u64 v[138:139], v[138:139], 0, v[154:155]
	v_or_b32_e32 v146, 16, v148
	v_lshl_add_u64 v[140:141], v[138:139], 0, s[94:95]
	v_add_co_u32_e32 v138, vcc, s10, v138
	v_ashrrev_i32_e32 v147, 31, v146
	s_nop 0
	v_addc_co_u32_e32 v139, vcc, 0, v139, vcc
	v_lshl_add_u64 v[188:189], s[42:43], 0, v[146:147]
	global_load_dwordx2 v[166:167], v[138:139], off offset:1024
	global_load_dwordx2 v[142:143], v[140:141], off offset:32
	global_load_dwordx2 v[194:195], v[140:141], off offset:64
	global_load_dwordx2 v[192:193], v[140:141], off offset:96
	v_mad_u64_u32 v[138:139], s[14:15], v188, s90, v[152:153]
	v_mov_b32_e32 v140, v139
	v_mad_u64_u32 v[140:141], s[14:15], v189, s90, v[140:141]
	v_mov_b32_e32 v139, v140
	v_lshl_add_u64 v[138:139], v[138:139], 0, s[6:7]
	v_lshl_add_u64 v[138:139], v[138:139], 0, v[154:155]
	v_or_b32_e32 v144, 32, v148
	v_lshl_add_u64 v[140:141], v[138:139], 0, s[94:95]
	v_add_co_u32_e32 v138, vcc, s10, v138
	v_ashrrev_i32_e32 v145, 31, v144
	s_nop 0
	v_addc_co_u32_e32 v139, vcc, 0, v139, vcc
	v_lshl_add_u64 v[178:179], s[42:43], 0, v[144:145]
	global_load_dwordx2 v[190:191], v[138:139], off offset:1024
	global_load_dwordx2 v[186:187], v[140:141], off offset:32
	global_load_dwordx2 v[184:185], v[140:141], off offset:64
	global_load_dwordx2 v[182:183], v[140:141], off offset:96
	v_mad_u64_u32 v[138:139], s[14:15], v178, s90, v[152:153]
	v_mov_b32_e32 v140, v139
	v_mad_u64_u32 v[140:141], s[14:15], v179, s90, v[140:141]
	v_mov_b32_e32 v139, v140
	v_lshl_add_u64 v[138:139], v[138:139], 0, s[6:7]
	v_lshl_add_u64 v[138:139], v[138:139], 0, v[154:155]
	v_lshl_add_u64 v[140:141], v[138:139], 0, s[94:95]
	v_add_co_u32_e32 v138, vcc, s10, v138
	s_nop 1
	v_addc_co_u32_e32 v139, vcc, 0, v139, vcc
	global_load_dwordx2 v[180:181], v[138:139], off offset:1024
	global_load_dwordx2 v[176:177], v[140:141], off offset:32
	global_load_dwordx2 v[174:175], v[140:141], off offset:64
	global_load_dwordx2 v[168:169], v[140:141], off offset:96
	v_or_b32_e32 v140, 48, v148
	v_ashrrev_i32_e32 v141, 31, v140
	v_lshl_add_u64 v[162:163], s[42:43], 0, v[140:141]
	v_mad_u64_u32 v[138:139], s[14:15], v162, s90, v[152:153]
	v_mov_b32_e32 v156, v139
	v_mad_u64_u32 v[156:157], s[14:15], v163, s90, v[156:157]
	v_mov_b32_e32 v139, v156
	v_lshl_add_u64 v[138:139], v[138:139], 0, s[6:7]
	v_lshl_add_u64 v[138:139], v[138:139], 0, v[154:155]
	v_lshl_add_u64 v[156:157], v[138:139], 0, s[94:95]
	v_add_co_u32_e32 v138, vcc, s10, v138
	s_nop 1
	v_addc_co_u32_e32 v139, vcc, 0, v139, vcc
	global_load_dwordx2 v[164:165], v[138:139], off offset:1024
	global_load_dwordx2 v[160:161], v[156:157], off offset:32
	global_load_dwordx2 v[158:159], v[156:157], off offset:64
	s_nop 0
	global_load_dwordx2 v[156:157], v[156:157], off offset:96
	s_waitcnt vmcnt(15)
	v_lshlrev_b32_e32 v139, 16, v166
	v_mul_f32_e32 v141, 0xbfb8aa3b, v139
	v_exp_f32_e32 v141, v141
	v_pk_add_f32 v[212:213], v[2:3], v[126:127]
	v_pk_add_f32 v[172:173], v[4:5], v[128:129]
	v_or_b32_e32 v138, s46, v0
	v_add_f32_e32 v141, 1.0, v141
	v_rcp_f32_e32 v141, v141
	v_pk_add_f32 v[198:199], v[10:11], v[118:119]
	v_mul_f32_e32 v139, v141, v139
	v_and_b32_e32 v141, 0xffff0000, v166
	v_mul_f32_e32 v145, 0xbfb8aa3b, v141
	v_exp_f32_e32 v145, v145
	v_mul_f32_e32 v139, v139, v212
	v_add_f32_e32 v145, 1.0, v145
	v_rcp_f32_e32 v145, v145
	s_nop 0
	v_mul_f32_e32 v141, v145, v141
	v_mul_f32_e32 v141, v141, v213
	v_cvt_pk_bf16_f32 v212, v139, v141
	v_lshlrev_b32_e32 v139, 16, v167
	v_mul_f32_e32 v141, 0xbfb8aa3b, v139
	v_exp_f32_e32 v141, v141
	s_nop 0
	v_add_f32_e32 v141, 1.0, v141
	v_rcp_f32_e32 v141, v141
	s_nop 0
	v_mul_f32_e32 v139, v141, v139
	v_and_b32_e32 v141, 0xffff0000, v167
	v_mul_f32_e32 v145, 0xbfb8aa3b, v141
	v_exp_f32_e32 v145, v145
	v_mul_f32_e32 v139, v139, v172
	v_mov_b64_e32 v[166:167], s[88:89]
	v_mad_u64_u32 v[214:215], s[14:15], v170, s4, v[166:167]
	v_add_f32_e32 v145, 1.0, v145
	v_rcp_f32_e32 v145, v145
	v_mov_b32_e32 v170, v215
	v_mad_u64_u32 v[170:171], s[14:15], v171, s4, v[170:171]
	v_mul_f32_e32 v141, v145, v141
	v_mul_f32_e32 v141, v141, v173
	v_cvt_pk_bf16_f32 v213, v139, v141
	s_waitcnt vmcnt(14)
	v_lshlrev_b32_e32 v141, 16, v142
	v_mul_f32_e32 v145, 0xbfb8aa3b, v141
	v_exp_f32_e32 v145, v145
	v_and_b32_e32 v142, 0xffff0000, v142
	v_ashrrev_i32_e32 v139, 31, v138
	v_mov_b32_e32 v215, v170
	v_add_f32_e32 v145, 1.0, v145
	v_rcp_f32_e32 v145, v145
	v_lshlrev_b64 v[170:171], 1, v[138:139]
	v_lshl_add_u64 v[172:173], v[214:215], 0, v[170:171]
	global_store_dwordx2 v[172:173], v[212:213], off
	v_mul_f32_e32 v141, v145, v141
	v_mul_f32_e32 v145, 0xbfb8aa3b, v142
	v_exp_f32_e32 v145, v145
	v_pk_add_f32 v[212:213], v[6:7], v[122:123]
	v_pk_add_f32 v[172:173], v[8:9], v[124:125]
	v_mul_f32_e32 v141, v141, v212
	v_add_f32_e32 v145, 1.0, v145
	v_rcp_f32_e32 v145, v145
	s_nop 0
	v_mul_f32_e32 v142, v145, v142
	v_mul_f32_e32 v142, v142, v213
	v_cvt_pk_bf16_f32 v212, v141, v142
	v_lshlrev_b32_e32 v141, 16, v143
	v_mul_f32_e32 v142, 0xbfb8aa3b, v141
	v_exp_f32_e32 v142, v142
	s_nop 0
	v_add_f32_e32 v142, 1.0, v142
	v_rcp_f32_e32 v142, v142
	s_nop 0
	v_mul_f32_e32 v141, v142, v141
	v_and_b32_e32 v142, 0xffff0000, v143
	v_mul_f32_e32 v143, 0xbfb8aa3b, v142
	v_exp_f32_e32 v143, v143
	v_mul_f32_e32 v141, v141, v172
	v_add_f32_e32 v143, 1.0, v143
	v_rcp_f32_e32 v143, v143
	s_nop 0
	v_mul_f32_e32 v142, v143, v142
	v_mul_f32_e32 v142, v142, v173
	v_cvt_pk_bf16_f32 v213, v141, v142
	v_lshl_add_u64 v[142:143], v[0:1], 0, s[46:47]
	s_waitcnt vmcnt(13)
	v_lshlrev_b32_e32 v0, 16, v194
	v_mul_f32_e32 v141, 0xbfb8aa3b, v0
	v_exp_f32_e32 v141, v141
	v_lshlrev_b64 v[172:173], 1, v[142:143]
	v_lshl_add_u64 v[214:215], v[214:215], 0, v[172:173]
	global_store_dwordx2 v[214:215], v[212:213], off offset:32
	v_add_f32_e32 v141, 1.0, v141
	v_rcp_f32_e32 v141, v141
	v_pk_add_f32 v[212:213], v[12:13], v[120:121]
	v_mul_f32_e32 v0, v141, v0
	v_and_b32_e32 v141, 0xffff0000, v194
	v_mul_f32_e32 v145, 0xbfb8aa3b, v141
	v_exp_f32_e32 v145, v145
	v_mul_f32_e32 v0, v0, v198
	v_add_f32_e32 v145, 1.0, v145
	v_rcp_f32_e32 v145, v145
	s_nop 0
	v_mul_f32_e32 v141, v145, v141
	v_mul_f32_e32 v141, v141, v199
	v_cvt_pk_bf16_f32 v194, v0, v141
	v_lshlrev_b32_e32 v0, 16, v195
	v_mul_f32_e32 v141, 0xbfb8aa3b, v0
	v_exp_f32_e32 v141, v141
	v_pk_add_f32 v[198:199], v[14:15], v[114:115]
	v_add_f32_e32 v141, 1.0, v141
	v_rcp_f32_e32 v141, v141
	s_nop 0
	v_mul_f32_e32 v0, v141, v0
	v_and_b32_e32 v141, 0xffff0000, v195
	v_mul_f32_e32 v145, 0xbfb8aa3b, v141
	v_exp_f32_e32 v145, v145
	v_mul_f32_e32 v0, v0, v212
	v_add_f32_e32 v145, 1.0, v145
	v_rcp_f32_e32 v145, v145
	s_nop 0
	v_mul_f32_e32 v141, v145, v141
	v_mul_f32_e32 v141, v141, v213
	v_cvt_pk_bf16_f32 v195, v0, v141
	s_waitcnt vmcnt(12)
	v_lshlrev_b32_e32 v0, 16, v192
	v_mul_f32_e32 v141, 0xbfb8aa3b, v0
	v_exp_f32_e32 v141, v141
	global_store_dwordx2 v[214:215], v[194:195], off offset:64
	v_pk_add_f32 v[194:195], v[16:17], v[116:117]
	v_add_f32_e32 v141, 1.0, v141
	v_rcp_f32_e32 v141, v141
	s_nop 0
	v_mul_f32_e32 v0, v141, v0
	v_and_b32_e32 v141, 0xffff0000, v192
	v_mul_f32_e32 v145, 0xbfb8aa3b, v141
	v_exp_f32_e32 v145, v145
	v_mul_f32_e32 v0, v0, v198
	v_add_f32_e32 v145, 1.0, v145
	v_rcp_f32_e32 v145, v145
	s_nop 0
	v_mul_f32_e32 v141, v145, v141
	v_mul_f32_e32 v141, v141, v199
	v_cvt_pk_bf16_f32 v192, v0, v141
	v_lshlrev_b32_e32 v0, 16, v193
	v_mul_f32_e32 v141, 0xbfb8aa3b, v0
	v_exp_f32_e32 v141, v141
	s_nop 0
	v_add_f32_e32 v141, 1.0, v141
	v_rcp_f32_e32 v141, v141
	s_nop 0
	v_mul_f32_e32 v0, v141, v0
	v_and_b32_e32 v141, 0xffff0000, v193
	v_mul_f32_e32 v145, 0xbfb8aa3b, v141
	v_exp_f32_e32 v145, v145
	v_mul_f32_e32 v0, v0, v194
	v_add_f32_e32 v145, 1.0, v145
	v_rcp_f32_e32 v145, v145
	s_nop 0
	v_mul_f32_e32 v141, v145, v141
	v_mul_f32_e32 v141, v141, v195
	v_cvt_pk_bf16_f32 v193, v0, v141
	s_waitcnt vmcnt(11)
	v_lshlrev_b32_e32 v0, 16, v190
	v_mul_f32_e32 v141, 0xbfb8aa3b, v0
	v_exp_f32_e32 v141, v141
	v_pk_add_f32 v[194:195], v[18:19], v[110:111]
	global_store_dwordx2 v[214:215], v[192:193], off offset:96
	v_pk_add_f32 v[192:193], v[20:21], v[112:113]
	v_add_f32_e32 v141, 1.0, v141
	v_rcp_f32_e32 v141, v141
	s_nop 0
	v_mul_f32_e32 v0, v141, v0
	v_and_b32_e32 v141, 0xffff0000, v190
	v_mul_f32_e32 v145, 0xbfb8aa3b, v141
	v_exp_f32_e32 v145, v145
	v_mul_f32_e32 v0, v0, v194
	v_add_f32_e32 v145, 1.0, v145
	v_rcp_f32_e32 v145, v145
	s_nop 0
	v_mul_f32_e32 v141, v145, v141
	v_mul_f32_e32 v141, v141, v195
	v_cvt_pk_bf16_f32 v190, v0, v141
	v_lshlrev_b32_e32 v0, 16, v191
	v_mul_f32_e32 v141, 0xbfb8aa3b, v0
	v_exp_f32_e32 v141, v141
	s_nop 0
	v_add_f32_e32 v141, 1.0, v141
	v_rcp_f32_e32 v141, v141
	s_nop 0
	v_mul_f32_e32 v0, v141, v0
	v_and_b32_e32 v141, 0xffff0000, v191
	v_mul_f32_e32 v145, 0xbfb8aa3b, v141
	v_exp_f32_e32 v145, v145
	v_mul_f32_e32 v0, v0, v192
	v_add_f32_e32 v145, 1.0, v145
	v_rcp_f32_e32 v145, v145
	s_nop 0
	v_mul_f32_e32 v141, v145, v141
	v_mul_f32_e32 v141, v141, v193
	v_mad_u64_u32 v[192:193], s[14:15], v188, s4, v[166:167]
	v_cvt_pk_bf16_f32 v191, v0, v141
	v_mov_b32_e32 v0, v193
	v_mad_u64_u32 v[188:189], s[14:15], v189, s4, v[0:1]
	s_waitcnt vmcnt(10)
	v_lshlrev_b32_e32 v0, 16, v186
	v_mul_f32_e32 v141, 0xbfb8aa3b, v0
	v_exp_f32_e32 v141, v141
	v_mov_b32_e32 v193, v188
	v_lshl_add_u64 v[188:189], v[192:193], 0, v[170:171]
	global_store_dwordx2 v[188:189], v[190:191], off
	v_add_f32_e32 v141, 1.0, v141
	v_rcp_f32_e32 v141, v141
	v_pk_add_f32 v[190:191], v[22:23], v[106:107]
	v_pk_add_f32 v[188:189], v[24:25], v[108:109]
	v_mul_f32_e32 v0, v141, v0
	v_and_b32_e32 v141, 0xffff0000, v186
	v_mul_f32_e32 v145, 0xbfb8aa3b, v141
	v_exp_f32_e32 v145, v145
	v_mul_f32_e32 v0, v0, v190
	v_add_f32_e32 v145, 1.0, v145
	v_rcp_f32_e32 v145, v145
	s_nop 0
	v_mul_f32_e32 v141, v145, v141
	v_mul_f32_e32 v141, v141, v191
	v_cvt_pk_bf16_f32 v186, v0, v141
	v_lshlrev_b32_e32 v0, 16, v187
	v_mul_f32_e32 v141, 0xbfb8aa3b, v0
	v_exp_f32_e32 v141, v141
	v_pk_add_f32 v[190:191], v[26:27], v[102:103]
	v_add_f32_e32 v141, 1.0, v141
	v_rcp_f32_e32 v141, v141
	s_nop 0
	v_mul_f32_e32 v0, v141, v0
	v_and_b32_e32 v141, 0xffff0000, v187
	v_mul_f32_e32 v145, 0xbfb8aa3b, v141
	v_exp_f32_e32 v145, v145
	v_mul_f32_e32 v0, v0, v188
	v_add_f32_e32 v145, 1.0, v145
	v_rcp_f32_e32 v145, v145
	s_nop 0
	v_mul_f32_e32 v141, v145, v141
	v_mul_f32_e32 v141, v141, v189
	v_cvt_pk_bf16_f32 v187, v0, v141
	s_waitcnt vmcnt(9)
	v_lshlrev_b32_e32 v0, 16, v184
	v_mul_f32_e32 v141, 0xbfb8aa3b, v0
	v_exp_f32_e32 v141, v141
	v_lshl_add_u64 v[188:189], v[192:193], 0, v[172:173]
	global_store_dwordx2 v[188:189], v[186:187], off offset:32
	v_pk_add_f32 v[186:187], v[28:29], v[104:105]
	v_add_f32_e32 v141, 1.0, v141
	v_rcp_f32_e32 v141, v141
	s_nop 0
	v_mul_f32_e32 v0, v141, v0
	v_and_b32_e32 v141, 0xffff0000, v184
	v_mul_f32_e32 v145, 0xbfb8aa3b, v141
	v_exp_f32_e32 v145, v145
	v_mul_f32_e32 v0, v0, v190
	v_add_f32_e32 v145, 1.0, v145
	v_rcp_f32_e32 v145, v145
	s_nop 0
	v_mul_f32_e32 v141, v145, v141
	v_mul_f32_e32 v141, v141, v191
	v_cvt_pk_bf16_f32 v184, v0, v141
	v_lshlrev_b32_e32 v0, 16, v185
	v_mul_f32_e32 v141, 0xbfb8aa3b, v0
	v_exp_f32_e32 v141, v141
	s_nop 0
	v_add_f32_e32 v141, 1.0, v141
	v_rcp_f32_e32 v141, v141
	s_nop 0
	v_mul_f32_e32 v0, v141, v0
	v_and_b32_e32 v141, 0xffff0000, v185
	v_mul_f32_e32 v145, 0xbfb8aa3b, v141
	v_exp_f32_e32 v145, v145
	v_mul_f32_e32 v0, v0, v186
	v_add_f32_e32 v145, 1.0, v145
	v_rcp_f32_e32 v145, v145
	s_nop 0
	v_mul_f32_e32 v141, v145, v141
	v_mul_f32_e32 v141, v141, v187
	v_cvt_pk_bf16_f32 v185, v0, v141
	s_waitcnt vmcnt(8)
	v_lshlrev_b32_e32 v0, 16, v182
	v_mul_f32_e32 v141, 0xbfb8aa3b, v0
	v_exp_f32_e32 v141, v141
	v_pk_add_f32 v[186:187], v[30:31], v[98:99]
	global_store_dwordx2 v[188:189], v[184:185], off offset:64
	v_pk_add_f32 v[184:185], v[32:33], v[100:101]
	v_add_f32_e32 v141, 1.0, v141
	v_rcp_f32_e32 v141, v141
	s_nop 0
	v_mul_f32_e32 v0, v141, v0
	v_and_b32_e32 v141, 0xffff0000, v182
	v_mul_f32_e32 v145, 0xbfb8aa3b, v141
	v_exp_f32_e32 v145, v145
	v_mul_f32_e32 v0, v0, v186
	v_add_f32_e32 v145, 1.0, v145
	v_rcp_f32_e32 v145, v145
	s_nop 0
	v_mul_f32_e32 v141, v145, v141
	v_mul_f32_e32 v141, v141, v187
	v_cvt_pk_bf16_f32 v182, v0, v141
	v_lshlrev_b32_e32 v0, 16, v183
	v_mul_f32_e32 v141, 0xbfb8aa3b, v0
	v_exp_f32_e32 v141, v141
	s_nop 0
	v_add_f32_e32 v141, 1.0, v141
	v_rcp_f32_e32 v141, v141
	s_nop 0
	v_mul_f32_e32 v0, v141, v0
	v_and_b32_e32 v141, 0xffff0000, v183
	v_mul_f32_e32 v145, 0xbfb8aa3b, v141
	v_exp_f32_e32 v145, v145
	v_mul_f32_e32 v0, v0, v184
	v_add_f32_e32 v145, 1.0, v145
	v_rcp_f32_e32 v145, v145
	s_nop 0
	v_mul_f32_e32 v141, v145, v141
	v_mul_f32_e32 v141, v141, v185
	v_cvt_pk_bf16_f32 v183, v0, v141
	s_waitcnt vmcnt(7)
	v_lshlrev_b32_e32 v0, 16, v180
	v_mul_f32_e32 v141, 0xbfb8aa3b, v0
	v_exp_f32_e32 v141, v141
	v_pk_add_f32 v[184:185], v[34:35], v[94:95]
	global_store_dwordx2 v[188:189], v[182:183], off offset:96
	v_pk_add_f32 v[182:183], v[36:37], v[96:97]
	v_add_f32_e32 v141, 1.0, v141
	v_rcp_f32_e32 v141, v141
	s_nop 0
	v_mul_f32_e32 v0, v141, v0
	v_and_b32_e32 v141, 0xffff0000, v180
	v_mul_f32_e32 v145, 0xbfb8aa3b, v141
	v_exp_f32_e32 v145, v145
	v_mul_f32_e32 v0, v0, v184
	v_add_f32_e32 v145, 1.0, v145
	v_rcp_f32_e32 v145, v145
	s_nop 0
	v_mul_f32_e32 v141, v145, v141
	v_mul_f32_e32 v141, v141, v185
	v_cvt_pk_bf16_f32 v180, v0, v141
	v_lshlrev_b32_e32 v0, 16, v181
	v_mul_f32_e32 v141, 0xbfb8aa3b, v0
	v_exp_f32_e32 v141, v141
	s_nop 0
	v_add_f32_e32 v141, 1.0, v141
	v_rcp_f32_e32 v141, v141
	s_nop 0
	v_mul_f32_e32 v0, v141, v0
	v_and_b32_e32 v141, 0xffff0000, v181
	v_mul_f32_e32 v145, 0xbfb8aa3b, v141
	v_exp_f32_e32 v145, v145
	v_mul_f32_e32 v0, v0, v182
	v_add_f32_e32 v145, 1.0, v145
	v_rcp_f32_e32 v145, v145
	s_nop 0
	v_mul_f32_e32 v141, v145, v141
	v_mul_f32_e32 v141, v141, v183
	v_mad_u64_u32 v[182:183], s[14:15], v178, s4, v[166:167]
	v_cvt_pk_bf16_f32 v181, v0, v141
	v_mov_b32_e32 v0, v183
	v_mad_u64_u32 v[178:179], s[14:15], v179, s4, v[0:1]
	s_waitcnt vmcnt(6)
	v_lshlrev_b32_e32 v0, 16, v176
	v_mul_f32_e32 v141, 0xbfb8aa3b, v0
	v_exp_f32_e32 v141, v141
	v_mov_b32_e32 v183, v178
	v_lshl_add_u64 v[178:179], v[182:183], 0, v[170:171]
	global_store_dwordx2 v[178:179], v[180:181], off
	v_add_f32_e32 v141, 1.0, v141
	v_rcp_f32_e32 v141, v141
	v_pk_add_f32 v[180:181], v[38:39], v[90:91]
	v_pk_add_f32 v[178:179], v[40:41], v[92:93]
	v_mad_u64_u32 v[166:167], s[14:15], v162, s4, v[166:167]
	v_mul_f32_e32 v0, v141, v0
	v_and_b32_e32 v141, 0xffff0000, v176
	v_mul_f32_e32 v145, 0xbfb8aa3b, v141
	v_exp_f32_e32 v145, v145
	v_mul_f32_e32 v0, v0, v180
	v_add_f32_e32 v145, 1.0, v145
	v_rcp_f32_e32 v145, v145
	s_nop 0
	v_mul_f32_e32 v141, v145, v141
	v_mul_f32_e32 v141, v141, v181
	v_cvt_pk_bf16_f32 v176, v0, v141
	v_lshlrev_b32_e32 v0, 16, v177
	v_mul_f32_e32 v141, 0xbfb8aa3b, v0
	v_exp_f32_e32 v141, v141
	v_pk_add_f32 v[180:181], v[42:43], v[86:87]
	v_add_f32_e32 v141, 1.0, v141
	v_rcp_f32_e32 v141, v141
	s_nop 0
	v_mul_f32_e32 v0, v141, v0
	v_and_b32_e32 v141, 0xffff0000, v177
	v_mul_f32_e32 v145, 0xbfb8aa3b, v141
	v_exp_f32_e32 v145, v145
	v_mul_f32_e32 v0, v0, v178
	v_add_f32_e32 v145, 1.0, v145
	v_rcp_f32_e32 v145, v145
	s_nop 0
	v_mul_f32_e32 v141, v145, v141
	v_mul_f32_e32 v141, v141, v179
	v_cvt_pk_bf16_f32 v177, v0, v141
	s_waitcnt vmcnt(5)
	v_lshlrev_b32_e32 v0, 16, v174
	v_mul_f32_e32 v141, 0xbfb8aa3b, v0
	v_exp_f32_e32 v141, v141
	v_lshl_add_u64 v[178:179], v[182:183], 0, v[172:173]
	global_store_dwordx2 v[178:179], v[176:177], off offset:32
	v_pk_add_f32 v[176:177], v[44:45], v[88:89]
	v_add_f32_e32 v141, 1.0, v141
	v_rcp_f32_e32 v141, v141
	s_nop 0
	v_mul_f32_e32 v0, v141, v0
	v_and_b32_e32 v141, 0xffff0000, v174
	v_mul_f32_e32 v145, 0xbfb8aa3b, v141
	v_exp_f32_e32 v145, v145
	v_mul_f32_e32 v0, v0, v180
	v_add_f32_e32 v145, 1.0, v145
	v_rcp_f32_e32 v145, v145
	s_nop 0
	v_mul_f32_e32 v141, v145, v141
	v_mul_f32_e32 v141, v141, v181
	v_cvt_pk_bf16_f32 v174, v0, v141
	v_lshlrev_b32_e32 v0, 16, v175
	v_mul_f32_e32 v141, 0xbfb8aa3b, v0
	v_exp_f32_e32 v141, v141
	s_nop 0
	v_add_f32_e32 v141, 1.0, v141
	v_rcp_f32_e32 v141, v141
	s_nop 0
	v_mul_f32_e32 v0, v141, v0
	v_and_b32_e32 v141, 0xffff0000, v175
	v_mul_f32_e32 v145, 0xbfb8aa3b, v141
	v_exp_f32_e32 v145, v145
	v_mul_f32_e32 v0, v0, v176
	v_add_f32_e32 v145, 1.0, v145
	v_rcp_f32_e32 v145, v145
	s_nop 0
	v_mul_f32_e32 v141, v145, v141
	v_mul_f32_e32 v141, v141, v177
	v_cvt_pk_bf16_f32 v175, v0, v141
	s_waitcnt vmcnt(4)
	v_lshlrev_b32_e32 v0, 16, v168
	v_mul_f32_e32 v141, 0xbfb8aa3b, v0
	v_exp_f32_e32 v141, v141
	v_pk_add_f32 v[176:177], v[46:47], v[82:83]
	global_store_dwordx2 v[178:179], v[174:175], off offset:64
	v_pk_add_f32 v[174:175], v[48:49], v[84:85]
	v_add_f32_e32 v141, 1.0, v141
	v_rcp_f32_e32 v141, v141
	s_nop 0
	v_mul_f32_e32 v0, v141, v0
	v_and_b32_e32 v141, 0xffff0000, v168
	v_mul_f32_e32 v145, 0xbfb8aa3b, v141
	v_exp_f32_e32 v145, v145
	v_mul_f32_e32 v0, v0, v176
	v_add_f32_e32 v145, 1.0, v145
	v_rcp_f32_e32 v145, v145
	s_nop 0
	v_mul_f32_e32 v141, v145, v141
	v_mul_f32_e32 v141, v141, v177
	v_cvt_pk_bf16_f32 v168, v0, v141
	v_lshlrev_b32_e32 v0, 16, v169
	v_mul_f32_e32 v141, 0xbfb8aa3b, v0
	v_exp_f32_e32 v141, v141
	s_nop 0
	v_add_f32_e32 v141, 1.0, v141
	v_rcp_f32_e32 v141, v141
	s_nop 0
	v_mul_f32_e32 v0, v141, v0
	v_and_b32_e32 v141, 0xffff0000, v169
	v_mul_f32_e32 v145, 0xbfb8aa3b, v141
	v_exp_f32_e32 v145, v145
	v_mul_f32_e32 v0, v0, v174
	v_add_f32_e32 v145, 1.0, v145
	v_rcp_f32_e32 v145, v145
	s_nop 0
	v_mul_f32_e32 v141, v145, v141
	v_mul_f32_e32 v141, v141, v175
	v_cvt_pk_bf16_f32 v169, v0, v141
	s_waitcnt vmcnt(3)
	v_lshlrev_b32_e32 v0, 16, v164
	v_mul_f32_e32 v141, 0xbfb8aa3b, v0
	v_exp_f32_e32 v141, v141
	v_pk_add_f32 v[174:175], v[50:51], v[78:79]
	global_store_dwordx2 v[178:179], v[168:169], off offset:96
	v_pk_add_f32 v[168:169], v[52:53], v[80:81]
	v_add_f32_e32 v141, 1.0, v141
	v_rcp_f32_e32 v141, v141
	s_nop 0
	v_mul_f32_e32 v0, v141, v0
	v_and_b32_e32 v141, 0xffff0000, v164
	v_mul_f32_e32 v145, 0xbfb8aa3b, v141
	v_exp_f32_e32 v145, v145
	v_mul_f32_e32 v0, v0, v174
	v_add_f32_e32 v145, 1.0, v145
	v_rcp_f32_e32 v145, v145
	s_nop 0
	v_mul_f32_e32 v141, v145, v141
	v_mul_f32_e32 v141, v141, v175
	v_cvt_pk_bf16_f32 v164, v0, v141
	v_lshlrev_b32_e32 v0, 16, v165
	v_mul_f32_e32 v141, 0xbfb8aa3b, v0
	v_exp_f32_e32 v141, v141
	s_nop 0
	v_add_f32_e32 v141, 1.0, v141
	v_rcp_f32_e32 v141, v141
	s_nop 0
	v_mul_f32_e32 v0, v141, v0
	v_and_b32_e32 v141, 0xffff0000, v165
	v_mul_f32_e32 v145, 0xbfb8aa3b, v141
	v_exp_f32_e32 v145, v145
	v_mul_f32_e32 v0, v0, v168
	v_add_f32_e32 v145, 1.0, v145
	v_rcp_f32_e32 v145, v145
	s_nop 0
	v_mul_f32_e32 v141, v145, v141
	v_mul_f32_e32 v141, v141, v169
	v_cvt_pk_bf16_f32 v165, v0, v141
	v_mov_b32_e32 v0, v167
	v_mad_u64_u32 v[162:163], s[14:15], v163, s4, v[0:1]
	s_waitcnt vmcnt(2)
	v_lshlrev_b32_e32 v0, 16, v160
	v_mul_f32_e32 v141, 0xbfb8aa3b, v0
	v_exp_f32_e32 v141, v141
	v_mov_b32_e32 v167, v162
	v_lshl_add_u64 v[162:163], v[166:167], 0, v[170:171]
	global_store_dwordx2 v[162:163], v[164:165], off
	v_add_f32_e32 v141, 1.0, v141
	v_rcp_f32_e32 v141, v141
	v_pk_add_f32 v[164:165], v[54:55], v[74:75]
	v_pk_add_f32 v[162:163], v[56:57], v[76:77]
	v_mul_f32_e32 v0, v141, v0
	v_and_b32_e32 v141, 0xffff0000, v160
	v_mul_f32_e32 v145, 0xbfb8aa3b, v141
	v_exp_f32_e32 v145, v145
	v_mul_f32_e32 v0, v0, v164
	v_add_f32_e32 v145, 1.0, v145
	v_rcp_f32_e32 v145, v145
	s_nop 0
	v_mul_f32_e32 v141, v145, v141
	v_mul_f32_e32 v141, v141, v165
	v_cvt_pk_bf16_f32 v160, v0, v141
	v_lshlrev_b32_e32 v0, 16, v161
	v_mul_f32_e32 v141, 0xbfb8aa3b, v0
	v_exp_f32_e32 v141, v141
	v_pk_add_f32 v[164:165], v[58:59], v[70:71]
	v_add_f32_e32 v141, 1.0, v141
	v_rcp_f32_e32 v141, v141
	s_nop 0
	v_mul_f32_e32 v0, v141, v0
	v_and_b32_e32 v141, 0xffff0000, v161
	v_mul_f32_e32 v145, 0xbfb8aa3b, v141
	v_exp_f32_e32 v145, v145
	v_mul_f32_e32 v0, v0, v162
	v_add_f32_e32 v145, 1.0, v145
	v_rcp_f32_e32 v145, v145
	s_nop 0
	v_mul_f32_e32 v141, v145, v141
	v_mul_f32_e32 v141, v141, v163
	v_cvt_pk_bf16_f32 v161, v0, v141
	s_waitcnt vmcnt(1)
	v_lshlrev_b32_e32 v0, 16, v158
	v_mul_f32_e32 v141, 0xbfb8aa3b, v0
	v_exp_f32_e32 v141, v141
	v_lshl_add_u64 v[162:163], v[166:167], 0, v[172:173]
	global_store_dwordx2 v[162:163], v[160:161], off offset:32
	v_pk_add_f32 v[160:161], v[60:61], v[72:73]
	v_add_f32_e32 v141, 1.0, v141
	v_rcp_f32_e32 v141, v141
	s_nop 0
	v_mul_f32_e32 v0, v141, v0
	v_and_b32_e32 v141, 0xffff0000, v158
	v_mul_f32_e32 v145, 0xbfb8aa3b, v141
	v_exp_f32_e32 v145, v145
	v_mul_f32_e32 v0, v0, v164
	v_add_f32_e32 v145, 1.0, v145
	v_rcp_f32_e32 v145, v145
	s_nop 0
	v_mul_f32_e32 v141, v145, v141
	v_mul_f32_e32 v141, v141, v165
	v_cvt_pk_bf16_f32 v158, v0, v141
	v_lshlrev_b32_e32 v0, 16, v159
	v_mul_f32_e32 v141, 0xbfb8aa3b, v0
	v_exp_f32_e32 v141, v141
	s_nop 0
	v_add_f32_e32 v141, 1.0, v141
	v_rcp_f32_e32 v141, v141
	s_nop 0
	v_mul_f32_e32 v0, v141, v0
	v_and_b32_e32 v141, 0xffff0000, v159
	v_mul_f32_e32 v145, 0xbfb8aa3b, v141
	v_exp_f32_e32 v145, v145
	v_mul_f32_e32 v0, v0, v160
	v_add_f32_e32 v145, 1.0, v145
	v_rcp_f32_e32 v145, v145
	s_nop 0
	v_mul_f32_e32 v141, v145, v141
	v_mul_f32_e32 v141, v141, v161
	v_cvt_pk_bf16_f32 v159, v0, v141
	s_waitcnt vmcnt(0)
	v_lshlrev_b32_e32 v0, 16, v156
	v_mul_f32_e32 v141, 0xbfb8aa3b, v0
	v_exp_f32_e32 v141, v141
	v_pk_add_f32 v[160:161], v[62:63], v[66:67]
	global_store_dwordx2 v[162:163], v[158:159], off offset:64
	v_pk_add_f32 v[158:159], v[64:65], v[68:69]
	v_add_f32_e32 v141, 1.0, v141
	v_rcp_f32_e32 v141, v141
	s_nop 0
	v_mul_f32_e32 v0, v141, v0
	v_and_b32_e32 v141, 0xffff0000, v156
	v_mul_f32_e32 v145, 0xbfb8aa3b, v141
	v_exp_f32_e32 v145, v145
	v_mul_f32_e32 v0, v0, v160
	v_add_f32_e32 v145, 1.0, v145
	v_rcp_f32_e32 v145, v145
	s_nop 0
	v_mul_f32_e32 v141, v145, v141
	v_mul_f32_e32 v141, v141, v161
	v_cvt_pk_bf16_f32 v156, v0, v141
	v_lshlrev_b32_e32 v0, 16, v157
	v_mul_f32_e32 v141, 0xbfb8aa3b, v0
	v_exp_f32_e32 v141, v141
	s_nop 0
	v_add_f32_e32 v141, 1.0, v141
	v_rcp_f32_e32 v141, v141
	s_nop 0
	v_mul_f32_e32 v0, v141, v0
	v_and_b32_e32 v141, 0xffff0000, v157
	v_mul_f32_e32 v145, 0xbfb8aa3b, v141
	v_exp_f32_e32 v145, v145
	v_mul_f32_e32 v0, v0, v158
	v_add_f32_e32 v145, 1.0, v145
	v_rcp_f32_e32 v145, v145
	s_nop 0
	v_mul_f32_e32 v141, v145, v141
	v_mul_f32_e32 v141, v141, v159
	v_cvt_pk_bf16_f32 v157, v0, v141
	global_store_dwordx2 v[162:163], v[156:157], off offset:96
	v_mul_lo_u32 v0, v248, s23
	v_or_b32_e32 v141, s11, v247
	v_sub_u32_e32 v0, v0, v141
	v_and_b32_e32 v141, 0xfff, v0
	v_or_b32_e32 v141, s40, v141
	v_mad_u64_u32 v[156:157], s[14:15], v141, s90, v[152:153]
	v_mad_i32_i24 v157, s41, v220, v157
	v_lshl_add_u64 v[156:157], v[156:157], 0, s[6:7]
	v_lshl_add_u64 v[156:157], v[156:157], 0, v[154:155]
	v_add_u32_e32 v141, 0xff0, v0
	v_lshl_add_u64 v[158:159], v[156:157], 0, s[94:95]
	v_add_co_u32_e32 v156, vcc, s10, v156
	v_and_b32_e32 v141, 0xfff, v141
	s_nop 0
	v_addc_co_u32_e32 v157, vcc, 0, v157, vcc
	v_or_b32_e32 v141, s40, v141
	global_load_dwordx2 v[182:183], v[156:157], off offset:1024
	global_load_dwordx2 v[180:181], v[158:159], off offset:32
	global_load_dwordx2 v[178:179], v[158:159], off offset:64
	global_load_dwordx2 v[176:177], v[158:159], off offset:96
	v_mad_u64_u32 v[156:157], s[14:15], v141, s90, v[152:153]
	v_mad_i32_i24 v157, s41, v220, v157
	v_lshl_add_u64 v[156:157], v[156:157], 0, s[6:7]
	v_lshl_add_u64 v[156:157], v[156:157], 0, v[154:155]
	v_add_u32_e32 v141, 0xfe0, v0
	v_lshl_add_u64 v[158:159], v[156:157], 0, s[94:95]
	v_add_co_u32_e32 v156, vcc, s10, v156
	v_and_b32_e32 v141, 0xfff, v141
	s_nop 0
	v_addc_co_u32_e32 v157, vcc, 0, v157, vcc
	v_or_b32_e32 v141, s40, v141
	v_add_u32_e32 v0, 0xfd0, v0
	global_load_dwordx2 v[174:175], v[156:157], off offset:1024
	global_load_dwordx2 v[172:173], v[158:159], off offset:32
	global_load_dwordx2 v[170:171], v[158:159], off offset:64
	global_load_dwordx2 v[168:169], v[158:159], off offset:96
	v_mad_u64_u32 v[156:157], s[14:15], v141, s90, v[152:153]
	v_and_b32_e32 v0, 0xfff, v0
	v_mad_i32_i24 v157, s41, v220, v157
	v_or_b32_e32 v0, s40, v0
	v_lshl_add_u64 v[156:157], v[156:157], 0, s[6:7]
	v_mad_u64_u32 v[152:153], s[14:15], v0, s90, v[152:153]
	v_lshl_add_u64 v[156:157], v[156:157], 0, v[154:155]
	v_mad_i32_i24 v153, s41, v220, v153
	v_lshl_add_u64 v[158:159], v[156:157], 0, s[94:95]
	v_add_co_u32_e32 v156, vcc, s10, v156
	v_lshl_add_u64 v[152:153], v[152:153], 0, s[6:7]
	s_nop 0
	v_addc_co_u32_e32 v157, vcc, 0, v157, vcc
	v_lshl_add_u64 v[152:153], v[152:153], 0, v[154:155]
	v_lshl_add_u64 v[184:185], v[152:153], 0, s[94:95]
	v_add_co_u32_e32 v152, vcc, 0x114ed000, v152
	global_load_dwordx2 v[166:167], v[156:157], off offset:1024
	global_load_dwordx2 v[164:165], v[158:159], off offset:32
	global_load_dwordx2 v[162:163], v[158:159], off offset:64
	global_load_dwordx2 v[160:161], v[158:159], off offset:96
	v_addc_co_u32_e32 v153, vcc, 0, v153, vcc
	global_load_dwordx2 v[158:159], v[152:153], off offset:1024
	global_load_dwordx2 v[156:157], v[184:185], off offset:32
	global_load_dwordx2 v[154:155], v[184:185], off offset:64
	s_nop 0
	global_load_dwordx2 v[152:153], v[184:185], off offset:96
	v_add_u32_e32 v0, s11, v148
	v_cmp_lt_i32_e32 vcc, 0, v0
	s_and_saveexec_b64 s[6:7], vcc
	s_cbranch_execz .LBB0_851
	s_waitcnt vmcnt(15)
	v_lshlrev_b32_e32 v184, 16, v182
	v_sub_u32_e32 v148, 0x1000, v0
	v_mul_f32_e32 v0, 0xbfb8aa3b, v184
	v_exp_f32_e32 v0, v0
	v_and_b32_e32 v185, 0xffff0000, v182
	v_lshlrev_b32_e32 v182, 16, v183
	v_sub_f32_e32 v127, v3, v127
	v_add_f32_e32 v0, 1.0, v0
	v_rcp_f32_e32 v186, v0
	v_mul_f32_e32 v0, 0xbfb8aa3b, v185
	v_exp_f32_e32 v0, v0
	v_sub_f32_e32 v126, v2, v126
	v_and_b32_e32 v183, 0xffff0000, v183
	v_sub_f32_e32 v129, v5, v129
	v_add_f32_e32 v0, 1.0, v0
	v_rcp_f32_e32 v187, v0
	v_mul_f32_e32 v0, 0xbfb8aa3b, v182
	v_exp_f32_e32 v0, v0
	v_sub_f32_e32 v128, v4, v128
	v_pk_mul_f32 v[184:185], v[186:187], v[184:185]
	v_ashrrev_i32_e32 v149, 31, v148
	v_add_f32_e32 v0, 1.0, v0
	v_pk_mul_f32 v[126:127], v[184:185], v[126:127]
	v_rcp_f32_e32 v184, v0
	v_mul_f32_e32 v0, 0xbfb8aa3b, v183
	v_exp_f32_e32 v0, v0
	v_lshl_add_u64 v[148:149], s[40:41], 0, v[148:149]
	v_cvt_pk_bf16_f32 v126, v126, v127
	v_sub_f32_e32 v123, v7, v123
	v_add_f32_e32 v0, 1.0, v0
	v_rcp_f32_e32 v185, v0
	v_sub_f32_e32 v122, v6, v122
	v_sub_f32_e32 v125, v9, v125
	v_sub_f32_e32 v124, v8, v124
	v_pk_mul_f32 v[182:183], v[184:185], v[182:183]
	v_sub_f32_e32 v119, v11, v119
	v_pk_mul_f32 v[128:129], v[182:183], v[128:129]
	v_sub_f32_e32 v118, v10, v118
	v_cvt_pk_bf16_f32 v127, v128, v129
	v_mov_b64_e32 v[128:129], s[88:89]
	v_mad_u64_u32 v[128:129], s[14:15], v148, s4, v[128:129]
	v_mad_i32_i24 v129, v149, s4, v129
	v_lshl_add_u64 v[148:149], v[138:139], 1, v[128:129]
	global_store_dwordx2 v[148:149], v[126:127], off
	s_waitcnt vmcnt(15)
	v_lshlrev_b32_e32 v126, 16, v180
	v_mul_f32_e32 v0, 0xbfb8aa3b, v126
	v_exp_f32_e32 v0, v0
	v_and_b32_e32 v127, 0xffff0000, v180
	v_sub_f32_e32 v121, v13, v121
	v_sub_f32_e32 v120, v12, v120
	v_add_f32_e32 v0, 1.0, v0
	v_rcp_f32_e32 v148, v0
	v_mul_f32_e32 v0, 0xbfb8aa3b, v127
	v_exp_f32_e32 v0, v0
	v_sub_f32_e32 v115, v15, v115
	v_sub_f32_e32 v114, v14, v114
	v_sub_f32_e32 v117, v17, v117
	v_add_f32_e32 v0, 1.0, v0
	v_rcp_f32_e32 v149, v0
	v_sub_f32_e32 v116, v16, v116
	v_pk_mul_f32 v[126:127], v[148:149], v[126:127]
	s_nop 0
	v_pk_mul_f32 v[122:123], v[126:127], v[122:123]
	v_lshlrev_b32_e32 v126, 16, v181
	v_mul_f32_e32 v0, 0xbfb8aa3b, v126
	v_exp_f32_e32 v0, v0
	v_and_b32_e32 v127, 0xffff0000, v181
	v_cvt_pk_bf16_f32 v122, v122, v123
	v_add_f32_e32 v0, 1.0, v0
	v_rcp_f32_e32 v148, v0
	v_mul_f32_e32 v0, 0xbfb8aa3b, v127
	v_exp_f32_e32 v0, v0
	s_nop 0
	v_add_f32_e32 v0, 1.0, v0
	v_rcp_f32_e32 v149, v0
	s_nop 0
	v_pk_mul_f32 v[126:127], v[148:149], v[126:127]
	s_nop 0
	v_pk_mul_f32 v[124:125], v[126:127], v[124:125]
	s_nop 0
	v_cvt_pk_bf16_f32 v123, v124, v125
	v_lshl_add_u64 v[124:125], v[142:143], 1, v[128:129]
	global_store_dwordx2 v[124:125], v[122:123], off offset:32
	s_waitcnt vmcnt(15)
	v_lshlrev_b32_e32 v122, 16, v178
	v_mul_f32_e32 v0, 0xbfb8aa3b, v122
	v_exp_f32_e32 v0, v0
	v_and_b32_e32 v123, 0xffff0000, v178
	v_add_f32_e32 v0, 1.0, v0
	v_rcp_f32_e32 v126, v0
	v_mul_f32_e32 v0, 0xbfb8aa3b, v123
	v_exp_f32_e32 v0, v0
	s_nop 0
	v_add_f32_e32 v0, 1.0, v0
	v_rcp_f32_e32 v127, v0
	s_nop 0
	v_pk_mul_f32 v[122:123], v[126:127], v[122:123]
	s_nop 0
	v_pk_mul_f32 v[118:119], v[122:123], v[118:119]
	v_lshlrev_b32_e32 v122, 16, v179
	v_mul_f32_e32 v0, 0xbfb8aa3b, v122
	v_exp_f32_e32 v0, v0
	v_and_b32_e32 v123, 0xffff0000, v179
	v_cvt_pk_bf16_f32 v118, v118, v119
	v_add_f32_e32 v0, 1.0, v0
	v_rcp_f32_e32 v126, v0
	v_mul_f32_e32 v0, 0xbfb8aa3b, v123
	v_exp_f32_e32 v0, v0
	s_nop 0
	v_add_f32_e32 v0, 1.0, v0
	v_rcp_f32_e32 v127, v0
	s_nop 0
	v_pk_mul_f32 v[122:123], v[126:127], v[122:123]
	s_nop 0
	v_pk_mul_f32 v[120:121], v[122:123], v[120:121]
	s_nop 0
	v_cvt_pk_bf16_f32 v119, v120, v121
	global_store_dwordx2 v[124:125], v[118:119], off offset:64
	s_waitcnt vmcnt(15)
	v_lshlrev_b32_e32 v118, 16, v176
	v_mul_f32_e32 v0, 0xbfb8aa3b, v118
	v_exp_f32_e32 v0, v0
	v_and_b32_e32 v119, 0xffff0000, v176
	v_add_f32_e32 v0, 1.0, v0
	v_rcp_f32_e32 v120, v0
	v_mul_f32_e32 v0, 0xbfb8aa3b, v119
	v_exp_f32_e32 v0, v0
	s_nop 0
	v_add_f32_e32 v0, 1.0, v0
	v_rcp_f32_e32 v121, v0
	s_nop 0
	v_pk_mul_f32 v[118:119], v[120:121], v[118:119]
	s_nop 0
	v_pk_mul_f32 v[114:115], v[118:119], v[114:115]
	v_lshlrev_b32_e32 v118, 16, v177
	v_mul_f32_e32 v0, 0xbfb8aa3b, v118
	v_exp_f32_e32 v0, v0
	v_and_b32_e32 v119, 0xffff0000, v177
	v_cvt_pk_bf16_f32 v114, v114, v115
	v_add_f32_e32 v0, 1.0, v0
	v_rcp_f32_e32 v120, v0
	v_mul_f32_e32 v0, 0xbfb8aa3b, v119
	v_exp_f32_e32 v0, v0
	s_nop 0
	v_add_f32_e32 v0, 1.0, v0
	v_rcp_f32_e32 v121, v0
	s_nop 0
	v_pk_mul_f32 v[118:119], v[120:121], v[118:119]
	s_nop 0
	v_pk_mul_f32 v[116:117], v[118:119], v[116:117]
	s_nop 0
	v_cvt_pk_bf16_f32 v115, v116, v117
	global_store_dwordx2 v[124:125], v[114:115], off offset:96

.LBB0_866:
	v_add_u32_e32 v0, v239, v235
	ds_read_b128 v[138:141], v246
	ds_read_b128 v[146:149], v246 offset:2048
	ds_read_b128 v[142:145], v243
	ds_read_b128 v[160:163], v0
	ds_read_b128 v[152:155], v244
	ds_read_b128 v[156:159], v245
	ds_read_b128 v[164:167], v246 offset:4096
	ds_read_b128 v[168:171], v246 offset:6144
	s_add_i32 s6, s6, 1
	s_cmp_lg_u32 s6, 64
	s_waitcnt lgkmcnt(5)
	v_mfma_f32_16x16x32_bf16 v[126:129], v[138:141], v[142:145], v[126:129]
	v_mfma_f32_16x16x32_bf16 v[122:125], v[146:149], v[142:145], v[122:125]
	s_waitcnt lgkmcnt(4)
	v_mfma_f32_16x16x32_bf16 v[110:113], v[138:141], v[160:163], v[110:113]
	v_mfma_f32_16x16x32_bf16 v[106:109], v[146:149], v[160:163], v[106:109]
	s_waitcnt lgkmcnt(1)
	v_mfma_f32_16x16x32_bf16 v[118:121], v[164:167], v[142:145], v[118:121]
	v_mfma_f32_16x16x32_bf16 v[102:105], v[164:167], v[160:163], v[102:105]
	v_mfma_f32_16x16x32_bf16 v[94:97], v[138:141], v[152:155], v[94:97]
	v_mfma_f32_16x16x32_bf16 v[90:93], v[146:149], v[152:155], v[90:93]
	s_waitcnt lgkmcnt(0)
	v_mfma_f32_16x16x32_bf16 v[114:117], v[168:171], v[142:145], v[114:117]
	v_mfma_f32_16x16x32_bf16 v[98:101], v[168:171], v[160:163], v[98:101]
	v_mfma_f32_16x16x32_bf16 v[86:89], v[164:167], v[152:155], v[86:89]
	v_mfma_f32_16x16x32_bf16 v[82:85], v[168:171], v[152:155], v[82:85]
	v_mfma_f32_16x16x32_bf16 v[78:81], v[138:141], v[156:159], v[78:81]
	v_mfma_f32_16x16x32_bf16 v[74:77], v[146:149], v[156:159], v[74:77]
	v_mfma_f32_16x16x32_bf16 v[70:73], v[164:167], v[156:159], v[70:73]
	v_mfma_f32_16x16x32_bf16 v[66:69], v[168:171], v[156:159], v[66:69]
	ds_read_b128 v[138:141], v246 offset:1024
	ds_read_b128 v[142:145], v246 offset:3072
	ds_read_b128 v[152:155], v246 offset:7168
	ds_read_b128 v[156:159], v246 offset:5120
	ds_read_b128 v[146:149], v244 offset:1024
	ds_read_b128 v[160:163], v245 offset:1024
	s_waitcnt lgkmcnt(1)
	v_mfma_f32_16x16x32_bf16 v[94:97], v[138:141], v[146:149], v[94:97]
	v_mfma_f32_16x16x32_bf16 v[90:93], v[142:145], v[146:149], v[90:93]
	v_mfma_f32_16x16x32_bf16 v[86:89], v[156:159], v[146:149], v[86:89]
	v_mfma_f32_16x16x32_bf16 v[82:85], v[152:155], v[146:149], v[82:85]
	ds_read_b128 v[146:149], v0 offset:1024
	s_waitcnt lgkmcnt(0)
	v_mfma_f32_16x16x32_bf16 v[110:113], v[138:141], v[146:149], v[110:113]
	v_mfma_f32_16x16x32_bf16 v[106:109], v[142:145], v[146:149], v[106:109]
	v_mfma_f32_16x16x32_bf16 v[102:105], v[156:159], v[146:149], v[102:105]
	v_mfma_f32_16x16x32_bf16 v[98:101], v[152:155], v[146:149], v[98:101]
	ds_read_b128 v[146:149], v243 offset:1024
	s_waitcnt lgkmcnt(0)
	v_mfma_f32_16x16x32_bf16 v[126:129], v[138:141], v[146:149], v[126:129]
	v_mfma_f32_16x16x32_bf16 v[122:125], v[142:145], v[146:149], v[122:125]
	v_mfma_f32_16x16x32_bf16 v[118:121], v[156:159], v[146:149], v[118:121]
	v_mfma_f32_16x16x32_bf16 v[114:117], v[152:155], v[146:149], v[114:117]
	v_mfma_f32_16x16x32_bf16 v[78:81], v[138:141], v[160:163], v[78:81]
	v_mfma_f32_16x16x32_bf16 v[74:77], v[142:145], v[160:163], v[74:77]
	v_mfma_f32_16x16x32_bf16 v[70:73], v[156:159], v[160:163], v[70:73]
	v_mfma_f32_16x16x32_bf16 v[66:69], v[152:155], v[160:163], v[66:69]
	s_cbranch_scc1 .LBB0_879
	s_cmp_eq_u32 s22, 0
	s_cbranch_scc1 .LBB0_877
	v_mov_b32_e32 v0, v196
	v_mov_b64_e32 v[152:153], s[30:31]
	v_and_b32_e32 v247, 15, v0
	v_ashrrev_i32_e32 v248, 7, v0
	v_lshl_or_b32 v148, v248, 6, v247
	v_ashrrev_i32_e32 v149, 31, v148
	v_and_b32_e32 v138, 64, v0
	v_lshrrev_b32_e32 v0, 2, v0
	v_lshl_add_u64 v[170:171], s[42:43], 0, v[148:149]
	v_and_or_b32 v0, v0, 12, v138
	v_mad_u64_u32 v[138:139], s[6:7], v170, s90, v[152:153]
	v_mov_b32_e32 v140, v139
	v_mad_u64_u32 v[140:141], s[6:7], v171, s90, v[140:141]
	v_mov_b32_e32 v139, v140
	s_lshl_b64 s[6:7], s[46:47], 1
	v_lshl_add_u64 v[138:139], v[138:139], 0, s[6:7]
	v_lshlrev_b32_e32 v154, 1, v0
	v_mov_b32_e32 v155, v1
	v_lshl_add_u64 v[138:139], v[138:139], 0, v[154:155]
	v_or_b32_e32 v146, 16, v148
	v_lshl_add_u64 v[140:141], v[138:139], 0, s[94:95]
	v_add_co_u32_e32 v138, vcc, s10, v138
	v_ashrrev_i32_e32 v147, 31, v146
	s_nop 0
	v_addc_co_u32_e32 v139, vcc, 0, v139, vcc
	v_lshl_add_u64 v[188:189], s[42:43], 0, v[146:147]
	global_load_dwordx2 v[166:167], v[138:139], off offset:1024
	global_load_dwordx2 v[142:143], v[140:141], off offset:32
	global_load_dwordx2 v[194:195], v[140:141], off offset:64
	global_load_dwordx2 v[192:193], v[140:141], off offset:96
	v_mad_u64_u32 v[138:139], s[14:15], v188, s90, v[152:153]
	v_mov_b32_e32 v140, v139
	v_mad_u64_u32 v[140:141], s[14:15], v189, s90, v[140:141]
	v_mov_b32_e32 v139, v140
	v_lshl_add_u64 v[138:139], v[138:139], 0, s[6:7]
	v_lshl_add_u64 v[138:139], v[138:139], 0, v[154:155]
	v_or_b32_e32 v144, 32, v148
	v_lshl_add_u64 v[140:141], v[138:139], 0, s[94:95]
	v_add_co_u32_e32 v138, vcc, s10, v138
	v_ashrrev_i32_e32 v145, 31, v144
	s_nop 0
	v_addc_co_u32_e32 v139, vcc, 0, v139, vcc
	v_lshl_add_u64 v[178:179], s[42:43], 0, v[144:145]
	global_load_dwordx2 v[190:191], v[138:139], off offset:1024
	global_load_dwordx2 v[186:187], v[140:141], off offset:32
	global_load_dwordx2 v[184:185], v[140:141], off offset:64
	global_load_dwordx2 v[182:183], v[140:141], off offset:96
	v_mad_u64_u32 v[138:139], s[14:15], v178, s90, v[152:153]
	v_mov_b32_e32 v140, v139
	v_mad_u64_u32 v[140:141], s[14:15], v179, s90, v[140:141]
	v_mov_b32_e32 v139, v140
	v_lshl_add_u64 v[138:139], v[138:139], 0, s[6:7]
	v_lshl_add_u64 v[138:139], v[138:139], 0, v[154:155]
	v_lshl_add_u64 v[140:141], v[138:139], 0, s[94:95]
	v_add_co_u32_e32 v138, vcc, s10, v138
	s_nop 1
	v_addc_co_u32_e32 v139, vcc, 0, v139, vcc
	global_load_dwordx2 v[180:181], v[138:139], off offset:1024
	global_load_dwordx2 v[176:177], v[140:141], off offset:32
	global_load_dwordx2 v[174:175], v[140:141], off offset:64
	global_load_dwordx2 v[168:169], v[140:141], off offset:96
	v_or_b32_e32 v140, 48, v148
	v_ashrrev_i32_e32 v141, 31, v140
	v_lshl_add_u64 v[162:163], s[42:43], 0, v[140:141]
	v_mad_u64_u32 v[138:139], s[14:15], v162, s90, v[152:153]
	v_mov_b32_e32 v156, v139
	v_mad_u64_u32 v[156:157], s[14:15], v163, s90, v[156:157]
	v_mov_b32_e32 v139, v156
	v_lshl_add_u64 v[138:139], v[138:139], 0, s[6:7]
	v_lshl_add_u64 v[138:139], v[138:139], 0, v[154:155]
	v_lshl_add_u64 v[156:157], v[138:139], 0, s[94:95]
	v_add_co_u32_e32 v138, vcc, s10, v138
	s_nop 1
	v_addc_co_u32_e32 v139, vcc, 0, v139, vcc
	global_load_dwordx2 v[164:165], v[138:139], off offset:1024
	global_load_dwordx2 v[160:161], v[156:157], off offset:32
	global_load_dwordx2 v[158:159], v[156:157], off offset:64
	s_nop 0
	global_load_dwordx2 v[156:157], v[156:157], off offset:96
	s_waitcnt vmcnt(15)
	v_lshlrev_b32_e32 v139, 16, v166
	v_mul_f32_e32 v141, 0xbfb8aa3b, v139
	v_exp_f32_e32 v141, v141
	v_pk_add_f32 v[198:199], v[2:3], v[126:127]
	v_pk_add_f32 v[172:173], v[4:5], v[128:129]
	v_or_b32_e32 v138, s46, v0
	v_add_f32_e32 v141, 1.0, v141
	v_rcp_f32_e32 v141, v141
	v_pk_add_f32 v[214:215], v[10:11], v[118:119]
	v_mul_f32_e32 v139, v141, v139
	v_and_b32_e32 v141, 0xffff0000, v166
	v_mul_f32_e32 v145, 0xbfb8aa3b, v141
	v_exp_f32_e32 v145, v145
	v_mul_f32_e32 v139, v139, v198
	v_add_f32_e32 v145, 1.0, v145
	v_rcp_f32_e32 v145, v145
	s_nop 0
	v_mul_f32_e32 v141, v145, v141
	v_mul_f32_e32 v141, v141, v199
	v_cvt_pk_bf16_f32 v198, v139, v141
	v_lshlrev_b32_e32 v139, 16, v167
	v_mul_f32_e32 v141, 0xbfb8aa3b, v139
	v_exp_f32_e32 v141, v141
	s_nop 0
	v_add_f32_e32 v141, 1.0, v141
	v_rcp_f32_e32 v141, v141
	s_nop 0
	v_mul_f32_e32 v139, v141, v139
	v_and_b32_e32 v141, 0xffff0000, v167
	v_mul_f32_e32 v145, 0xbfb8aa3b, v141
	v_exp_f32_e32 v145, v145
	v_mul_f32_e32 v139, v139, v172
	v_mov_b64_e32 v[166:167], s[88:89]
	v_mad_u64_u32 v[212:213], s[14:15], v170, s4, v[166:167]
	v_add_f32_e32 v145, 1.0, v145
	v_rcp_f32_e32 v145, v145
	v_mov_b32_e32 v170, v213
	v_mad_u64_u32 v[170:171], s[14:15], v171, s4, v[170:171]
	v_mul_f32_e32 v141, v145, v141
	v_mul_f32_e32 v141, v141, v173
	v_cvt_pk_bf16_f32 v199, v139, v141
	s_waitcnt vmcnt(14)
	v_lshlrev_b32_e32 v141, 16, v142
	v_mul_f32_e32 v145, 0xbfb8aa3b, v141
	v_exp_f32_e32 v145, v145
	v_and_b32_e32 v142, 0xffff0000, v142
	v_ashrrev_i32_e32 v139, 31, v138
	v_mov_b32_e32 v213, v170
	v_add_f32_e32 v145, 1.0, v145
	v_rcp_f32_e32 v145, v145
	v_lshlrev_b64 v[170:171], 1, v[138:139]
	v_lshl_add_u64 v[172:173], v[212:213], 0, v[170:171]
	global_store_dwordx2 v[172:173], v[198:199], off
	v_mul_f32_e32 v141, v145, v141
	v_mul_f32_e32 v145, 0xbfb8aa3b, v142
	v_exp_f32_e32 v145, v145
	v_pk_add_f32 v[198:199], v[6:7], v[122:123]
	v_pk_add_f32 v[172:173], v[8:9], v[124:125]
	v_mul_f32_e32 v141, v141, v198
	v_add_f32_e32 v145, 1.0, v145
	v_rcp_f32_e32 v145, v145
	s_nop 0
	v_mul_f32_e32 v142, v145, v142
	v_mul_f32_e32 v142, v142, v199
	v_cvt_pk_bf16_f32 v198, v141, v142
	v_lshlrev_b32_e32 v141, 16, v143
	v_mul_f32_e32 v142, 0xbfb8aa3b, v141
	v_exp_f32_e32 v142, v142
	s_nop 0
	v_add_f32_e32 v142, 1.0, v142
	v_rcp_f32_e32 v142, v142
	s_nop 0
	v_mul_f32_e32 v141, v142, v141
	v_and_b32_e32 v142, 0xffff0000, v143
	v_mul_f32_e32 v143, 0xbfb8aa3b, v142
	v_exp_f32_e32 v143, v143
	v_mul_f32_e32 v141, v141, v172
	v_add_f32_e32 v143, 1.0, v143
	v_rcp_f32_e32 v143, v143
	s_nop 0
	v_mul_f32_e32 v142, v143, v142
	v_mul_f32_e32 v142, v142, v173
	v_cvt_pk_bf16_f32 v199, v141, v142
	v_lshl_add_u64 v[142:143], v[0:1], 0, s[46:47]
	s_waitcnt vmcnt(13)
	v_lshlrev_b32_e32 v0, 16, v194
	v_mul_f32_e32 v141, 0xbfb8aa3b, v0
	v_exp_f32_e32 v141, v141
	v_lshlrev_b64 v[172:173], 1, v[142:143]
	v_lshl_add_u64 v[212:213], v[212:213], 0, v[172:173]
	global_store_dwordx2 v[212:213], v[198:199], off offset:32
	v_add_f32_e32 v141, 1.0, v141
	v_rcp_f32_e32 v141, v141
	v_pk_add_f32 v[198:199], v[12:13], v[120:121]
	v_mul_f32_e32 v0, v141, v0
	v_and_b32_e32 v141, 0xffff0000, v194
	v_mul_f32_e32 v145, 0xbfb8aa3b, v141
	v_exp_f32_e32 v145, v145
	v_mul_f32_e32 v0, v0, v214
	v_add_f32_e32 v145, 1.0, v145
	v_rcp_f32_e32 v145, v145
	s_nop 0
	v_mul_f32_e32 v141, v145, v141
	v_mul_f32_e32 v141, v141, v215
	v_cvt_pk_bf16_f32 v194, v0, v141
	v_lshlrev_b32_e32 v0, 16, v195
	v_mul_f32_e32 v141, 0xbfb8aa3b, v0
	v_exp_f32_e32 v141, v141
	s_nop 0
	v_add_f32_e32 v141, 1.0, v141
	v_rcp_f32_e32 v141, v141
	s_nop 0
	v_mul_f32_e32 v0, v141, v0
	v_and_b32_e32 v141, 0xffff0000, v195
	v_mul_f32_e32 v145, 0xbfb8aa3b, v141
	v_exp_f32_e32 v145, v145
	v_mul_f32_e32 v0, v0, v198
	v_add_f32_e32 v145, 1.0, v145
	v_rcp_f32_e32 v145, v145
	s_nop 0
	v_mul_f32_e32 v141, v145, v141
	v_mul_f32_e32 v141, v141, v199
	v_cvt_pk_bf16_f32 v195, v0, v141
	s_waitcnt vmcnt(12)
	v_lshlrev_b32_e32 v0, 16, v192
	v_mul_f32_e32 v141, 0xbfb8aa3b, v0
	v_exp_f32_e32 v141, v141
	v_pk_add_f32 v[198:199], v[14:15], v[114:115]
	global_store_dwordx2 v[212:213], v[194:195], off offset:64
	v_pk_add_f32 v[194:195], v[16:17], v[116:117]
	v_add_f32_e32 v141, 1.0, v141
	v_rcp_f32_e32 v141, v141
	s_nop 0
	v_mul_f32_e32 v0, v141, v0
	v_and_b32_e32 v141, 0xffff0000, v192
	v_mul_f32_e32 v145, 0xbfb8aa3b, v141
	v_exp_f32_e32 v145, v145
	v_mul_f32_e32 v0, v0, v198
	v_add_f32_e32 v145, 1.0, v145
	v_rcp_f32_e32 v145, v145
	s_nop 0
	v_mul_f32_e32 v141, v145, v141
	v_mul_f32_e32 v141, v141, v199
	v_cvt_pk_bf16_f32 v192, v0, v141
	v_lshlrev_b32_e32 v0, 16, v193
	v_mul_f32_e32 v141, 0xbfb8aa3b, v0
	v_exp_f32_e32 v141, v141
	s_nop 0
	v_add_f32_e32 v141, 1.0, v141
	v_rcp_f32_e32 v141, v141
	s_nop 0
	v_mul_f32_e32 v0, v141, v0
	v_and_b32_e32 v141, 0xffff0000, v193
	v_mul_f32_e32 v145, 0xbfb8aa3b, v141
	v_exp_f32_e32 v145, v145
	v_mul_f32_e32 v0, v0, v194
	v_add_f32_e32 v145, 1.0, v145
	v_rcp_f32_e32 v145, v145
	s_nop 0
	v_mul_f32_e32 v141, v145, v141
	v_mul_f32_e32 v141, v141, v195
	v_cvt_pk_bf16_f32 v193, v0, v141
	s_waitcnt vmcnt(11)
	v_lshlrev_b32_e32 v0, 16, v190
	v_mul_f32_e32 v141, 0xbfb8aa3b, v0
	v_exp_f32_e32 v141, v141
	v_pk_add_f32 v[194:195], v[18:19], v[110:111]
	global_store_dwordx2 v[212:213], v[192:193], off offset:96
	v_pk_add_f32 v[192:193], v[20:21], v[112:113]
	v_add_f32_e32 v141, 1.0, v141
	v_rcp_f32_e32 v141, v141
	s_nop 0
	v_mul_f32_e32 v0, v141, v0
	v_and_b32_e32 v141, 0xffff0000, v190
	v_mul_f32_e32 v145, 0xbfb8aa3b, v141
	v_exp_f32_e32 v145, v145
	v_mul_f32_e32 v0, v0, v194
	v_add_f32_e32 v145, 1.0, v145
	v_rcp_f32_e32 v145, v145
	s_nop 0
	v_mul_f32_e32 v141, v145, v141
	v_mul_f32_e32 v141, v141, v195
	v_cvt_pk_bf16_f32 v190, v0, v141
	v_lshlrev_b32_e32 v0, 16, v191
	v_mul_f32_e32 v141, 0xbfb8aa3b, v0
	v_exp_f32_e32 v141, v141
	s_nop 0
	v_add_f32_e32 v141, 1.0, v141
	v_rcp_f32_e32 v141, v141
	s_nop 0
	v_mul_f32_e32 v0, v141, v0
	v_and_b32_e32 v141, 0xffff0000, v191
	v_mul_f32_e32 v145, 0xbfb8aa3b, v141
	v_exp_f32_e32 v145, v145
	v_mul_f32_e32 v0, v0, v192
	v_add_f32_e32 v145, 1.0, v145
	v_rcp_f32_e32 v145, v145
	s_nop 0
	v_mul_f32_e32 v141, v145, v141
	v_mul_f32_e32 v141, v141, v193
	v_mad_u64_u32 v[192:193], s[14:15], v188, s4, v[166:167]
	v_cvt_pk_bf16_f32 v191, v0, v141
	v_mov_b32_e32 v0, v193
	v_mad_u64_u32 v[188:189], s[14:15], v189, s4, v[0:1]
	s_waitcnt vmcnt(10)
	v_lshlrev_b32_e32 v0, 16, v186
	v_mul_f32_e32 v141, 0xbfb8aa3b, v0
	v_exp_f32_e32 v141, v141
	v_mov_b32_e32 v193, v188
	v_lshl_add_u64 v[188:189], v[192:193], 0, v[170:171]
	global_store_dwordx2 v[188:189], v[190:191], off
	v_add_f32_e32 v141, 1.0, v141
	v_rcp_f32_e32 v141, v141
	v_pk_add_f32 v[190:191], v[22:23], v[106:107]
	v_pk_add_f32 v[188:189], v[24:25], v[108:109]
	v_mul_f32_e32 v0, v141, v0
	v_and_b32_e32 v141, 0xffff0000, v186
	v_mul_f32_e32 v145, 0xbfb8aa3b, v141
	v_exp_f32_e32 v145, v145
	v_mul_f32_e32 v0, v0, v190
	v_add_f32_e32 v145, 1.0, v145
	v_rcp_f32_e32 v145, v145
	s_nop 0
	v_mul_f32_e32 v141, v145, v141
	v_mul_f32_e32 v141, v141, v191
	v_cvt_pk_bf16_f32 v186, v0, v141
	v_lshlrev_b32_e32 v0, 16, v187
	v_mul_f32_e32 v141, 0xbfb8aa3b, v0
	v_exp_f32_e32 v141, v141
	v_pk_add_f32 v[190:191], v[26:27], v[102:103]
	v_add_f32_e32 v141, 1.0, v141
	v_rcp_f32_e32 v141, v141
	s_nop 0
	v_mul_f32_e32 v0, v141, v0
	v_and_b32_e32 v141, 0xffff0000, v187
	v_mul_f32_e32 v145, 0xbfb8aa3b, v141
	v_exp_f32_e32 v145, v145
	v_mul_f32_e32 v0, v0, v188
	v_add_f32_e32 v145, 1.0, v145
	v_rcp_f32_e32 v145, v145
	s_nop 0
	v_mul_f32_e32 v141, v145, v141
	v_mul_f32_e32 v141, v141, v189
	v_cvt_pk_bf16_f32 v187, v0, v141
	s_waitcnt vmcnt(9)
	v_lshlrev_b32_e32 v0, 16, v184
	v_mul_f32_e32 v141, 0xbfb8aa3b, v0
	v_exp_f32_e32 v141, v141
	v_lshl_add_u64 v[188:189], v[192:193], 0, v[172:173]
	global_store_dwordx2 v[188:189], v[186:187], off offset:32
	v_pk_add_f32 v[186:187], v[28:29], v[104:105]
	v_add_f32_e32 v141, 1.0, v141
	v_rcp_f32_e32 v141, v141
	s_nop 0
	v_mul_f32_e32 v0, v141, v0
	v_and_b32_e32 v141, 0xffff0000, v184
	v_mul_f32_e32 v145, 0xbfb8aa3b, v141
	v_exp_f32_e32 v145, v145
	v_mul_f32_e32 v0, v0, v190
	v_add_f32_e32 v145, 1.0, v145
	v_rcp_f32_e32 v145, v145
	s_nop 0
	v_mul_f32_e32 v141, v145, v141
	v_mul_f32_e32 v141, v141, v191
	v_cvt_pk_bf16_f32 v184, v0, v141
	v_lshlrev_b32_e32 v0, 16, v185
	v_mul_f32_e32 v141, 0xbfb8aa3b, v0
	v_exp_f32_e32 v141, v141
	s_nop 0
	v_add_f32_e32 v141, 1.0, v141
	v_rcp_f32_e32 v141, v141
	s_nop 0
	v_mul_f32_e32 v0, v141, v0
	v_and_b32_e32 v141, 0xffff0000, v185
	v_mul_f32_e32 v145, 0xbfb8aa3b, v141
	v_exp_f32_e32 v145, v145
	v_mul_f32_e32 v0, v0, v186
	v_add_f32_e32 v145, 1.0, v145
	v_rcp_f32_e32 v145, v145
	s_nop 0
	v_mul_f32_e32 v141, v145, v141
	v_mul_f32_e32 v141, v141, v187
	v_cvt_pk_bf16_f32 v185, v0, v141
	s_waitcnt vmcnt(8)
	v_lshlrev_b32_e32 v0, 16, v182
	v_mul_f32_e32 v141, 0xbfb8aa3b, v0
	v_exp_f32_e32 v141, v141
	v_pk_add_f32 v[186:187], v[30:31], v[98:99]
	global_store_dwordx2 v[188:189], v[184:185], off offset:64
	v_pk_add_f32 v[184:185], v[32:33], v[100:101]
	v_add_f32_e32 v141, 1.0, v141
	v_rcp_f32_e32 v141, v141
	s_nop 0
	v_mul_f32_e32 v0, v141, v0
	v_and_b32_e32 v141, 0xffff0000, v182
	v_mul_f32_e32 v145, 0xbfb8aa3b, v141
	v_exp_f32_e32 v145, v145
	v_mul_f32_e32 v0, v0, v186
	v_add_f32_e32 v145, 1.0, v145
	v_rcp_f32_e32 v145, v145
	s_nop 0
	v_mul_f32_e32 v141, v145, v141
	v_mul_f32_e32 v141, v141, v187
	v_cvt_pk_bf16_f32 v182, v0, v141
	v_lshlrev_b32_e32 v0, 16, v183
	v_mul_f32_e32 v141, 0xbfb8aa3b, v0
	v_exp_f32_e32 v141, v141
	s_nop 0
	v_add_f32_e32 v141, 1.0, v141
	v_rcp_f32_e32 v141, v141
	s_nop 0
	v_mul_f32_e32 v0, v141, v0
	v_and_b32_e32 v141, 0xffff0000, v183
	v_mul_f32_e32 v145, 0xbfb8aa3b, v141
	v_exp_f32_e32 v145, v145
	v_mul_f32_e32 v0, v0, v184
	v_add_f32_e32 v145, 1.0, v145
	v_rcp_f32_e32 v145, v145
	s_nop 0
	v_mul_f32_e32 v141, v145, v141
	v_mul_f32_e32 v141, v141, v185
	v_cvt_pk_bf16_f32 v183, v0, v141
	s_waitcnt vmcnt(7)
	v_lshlrev_b32_e32 v0, 16, v180
	v_mul_f32_e32 v141, 0xbfb8aa3b, v0
	v_exp_f32_e32 v141, v141
	v_pk_add_f32 v[184:185], v[34:35], v[94:95]
	global_store_dwordx2 v[188:189], v[182:183], off offset:96
	v_pk_add_f32 v[182:183], v[36:37], v[96:97]
	v_add_f32_e32 v141, 1.0, v141
	v_rcp_f32_e32 v141, v141
	s_nop 0
	v_mul_f32_e32 v0, v141, v0
	v_and_b32_e32 v141, 0xffff0000, v180
	v_mul_f32_e32 v145, 0xbfb8aa3b, v141
	v_exp_f32_e32 v145, v145
	v_mul_f32_e32 v0, v0, v184
	v_add_f32_e32 v145, 1.0, v145
	v_rcp_f32_e32 v145, v145
	s_nop 0
	v_mul_f32_e32 v141, v145, v141
	v_mul_f32_e32 v141, v141, v185
	v_cvt_pk_bf16_f32 v180, v0, v141
	v_lshlrev_b32_e32 v0, 16, v181
	v_mul_f32_e32 v141, 0xbfb8aa3b, v0
	v_exp_f32_e32 v141, v141
	s_nop 0
	v_add_f32_e32 v141, 1.0, v141
	v_rcp_f32_e32 v141, v141
	s_nop 0
	v_mul_f32_e32 v0, v141, v0
	v_and_b32_e32 v141, 0xffff0000, v181
	v_mul_f32_e32 v145, 0xbfb8aa3b, v141
	v_exp_f32_e32 v145, v145
	v_mul_f32_e32 v0, v0, v182
	v_add_f32_e32 v145, 1.0, v145
	v_rcp_f32_e32 v145, v145
	s_nop 0
	v_mul_f32_e32 v141, v145, v141
	v_mul_f32_e32 v141, v141, v183
	v_mad_u64_u32 v[182:183], s[14:15], v178, s4, v[166:167]
	v_cvt_pk_bf16_f32 v181, v0, v141
	v_mov_b32_e32 v0, v183
	v_mad_u64_u32 v[178:179], s[14:15], v179, s4, v[0:1]
	s_waitcnt vmcnt(6)
	v_lshlrev_b32_e32 v0, 16, v176
	v_mul_f32_e32 v141, 0xbfb8aa3b, v0
	v_exp_f32_e32 v141, v141
	v_mov_b32_e32 v183, v178
	v_lshl_add_u64 v[178:179], v[182:183], 0, v[170:171]
	global_store_dwordx2 v[178:179], v[180:181], off
	v_add_f32_e32 v141, 1.0, v141
	v_rcp_f32_e32 v141, v141
	v_pk_add_f32 v[180:181], v[38:39], v[90:91]
	v_pk_add_f32 v[178:179], v[40:41], v[92:93]
	v_mad_u64_u32 v[166:167], s[14:15], v162, s4, v[166:167]
	v_mul_f32_e32 v0, v141, v0
	v_and_b32_e32 v141, 0xffff0000, v176
	v_mul_f32_e32 v145, 0xbfb8aa3b, v141
	v_exp_f32_e32 v145, v145
	v_mul_f32_e32 v0, v0, v180
	v_add_f32_e32 v145, 1.0, v145
	v_rcp_f32_e32 v145, v145
	s_nop 0
	v_mul_f32_e32 v141, v145, v141
	v_mul_f32_e32 v141, v141, v181
	v_cvt_pk_bf16_f32 v176, v0, v141
	v_lshlrev_b32_e32 v0, 16, v177
	v_mul_f32_e32 v141, 0xbfb8aa3b, v0
	v_exp_f32_e32 v141, v141
	v_pk_add_f32 v[180:181], v[42:43], v[86:87]
	v_add_f32_e32 v141, 1.0, v141
	v_rcp_f32_e32 v141, v141
	s_nop 0
	v_mul_f32_e32 v0, v141, v0
	v_and_b32_e32 v141, 0xffff0000, v177
	v_mul_f32_e32 v145, 0xbfb8aa3b, v141
	v_exp_f32_e32 v145, v145
	v_mul_f32_e32 v0, v0, v178
	v_add_f32_e32 v145, 1.0, v145
	v_rcp_f32_e32 v145, v145
	s_nop 0
	v_mul_f32_e32 v141, v145, v141
	v_mul_f32_e32 v141, v141, v179
	v_cvt_pk_bf16_f32 v177, v0, v141
	s_waitcnt vmcnt(5)
	v_lshlrev_b32_e32 v0, 16, v174
	v_mul_f32_e32 v141, 0xbfb8aa3b, v0
	v_exp_f32_e32 v141, v141
	v_lshl_add_u64 v[178:179], v[182:183], 0, v[172:173]
	global_store_dwordx2 v[178:179], v[176:177], off offset:32
	v_pk_add_f32 v[176:177], v[44:45], v[88:89]
	v_add_f32_e32 v141, 1.0, v141
	v_rcp_f32_e32 v141, v141
	s_nop 0
	v_mul_f32_e32 v0, v141, v0
	v_and_b32_e32 v141, 0xffff0000, v174
	v_mul_f32_e32 v145, 0xbfb8aa3b, v141
	v_exp_f32_e32 v145, v145
	v_mul_f32_e32 v0, v0, v180
	v_add_f32_e32 v145, 1.0, v145
	v_rcp_f32_e32 v145, v145
	s_nop 0
	v_mul_f32_e32 v141, v145, v141
	v_mul_f32_e32 v141, v141, v181
	v_cvt_pk_bf16_f32 v174, v0, v141
	v_lshlrev_b32_e32 v0, 16, v175
	v_mul_f32_e32 v141, 0xbfb8aa3b, v0
	v_exp_f32_e32 v141, v141
	s_nop 0
	v_add_f32_e32 v141, 1.0, v141
	v_rcp_f32_e32 v141, v141
	s_nop 0
	v_mul_f32_e32 v0, v141, v0
	v_and_b32_e32 v141, 0xffff0000, v175
	v_mul_f32_e32 v145, 0xbfb8aa3b, v141
	v_exp_f32_e32 v145, v145
	v_mul_f32_e32 v0, v0, v176
	v_add_f32_e32 v145, 1.0, v145
	v_rcp_f32_e32 v145, v145
	s_nop 0
	v_mul_f32_e32 v141, v145, v141
	v_mul_f32_e32 v141, v141, v177
	v_cvt_pk_bf16_f32 v175, v0, v141
	s_waitcnt vmcnt(4)
	v_lshlrev_b32_e32 v0, 16, v168
	v_mul_f32_e32 v141, 0xbfb8aa3b, v0
	v_exp_f32_e32 v141, v141
	v_pk_add_f32 v[176:177], v[46:47], v[82:83]
	global_store_dwordx2 v[178:179], v[174:175], off offset:64
	v_pk_add_f32 v[174:175], v[48:49], v[84:85]
	v_add_f32_e32 v141, 1.0, v141
	v_rcp_f32_e32 v141, v141
	s_nop 0
	v_mul_f32_e32 v0, v141, v0
	v_and_b32_e32 v141, 0xffff0000, v168
	v_mul_f32_e32 v145, 0xbfb8aa3b, v141
	v_exp_f32_e32 v145, v145
	v_mul_f32_e32 v0, v0, v176
	v_add_f32_e32 v145, 1.0, v145
	v_rcp_f32_e32 v145, v145
	s_nop 0
	v_mul_f32_e32 v141, v145, v141
	v_mul_f32_e32 v141, v141, v177
	v_cvt_pk_bf16_f32 v168, v0, v141
	v_lshlrev_b32_e32 v0, 16, v169
	v_mul_f32_e32 v141, 0xbfb8aa3b, v0
	v_exp_f32_e32 v141, v141
	s_nop 0
	v_add_f32_e32 v141, 1.0, v141
	v_rcp_f32_e32 v141, v141
	s_nop 0
	v_mul_f32_e32 v0, v141, v0
	v_and_b32_e32 v141, 0xffff0000, v169
	v_mul_f32_e32 v145, 0xbfb8aa3b, v141
	v_exp_f32_e32 v145, v145
	v_mul_f32_e32 v0, v0, v174
	v_add_f32_e32 v145, 1.0, v145
	v_rcp_f32_e32 v145, v145
	s_nop 0
	v_mul_f32_e32 v141, v145, v141
	v_mul_f32_e32 v141, v141, v175
	v_cvt_pk_bf16_f32 v169, v0, v141
	s_waitcnt vmcnt(3)
	v_lshlrev_b32_e32 v0, 16, v164
	v_mul_f32_e32 v141, 0xbfb8aa3b, v0
	v_exp_f32_e32 v141, v141
	v_pk_add_f32 v[174:175], v[50:51], v[78:79]
	global_store_dwordx2 v[178:179], v[168:169], off offset:96
	v_pk_add_f32 v[168:169], v[52:53], v[80:81]
	v_add_f32_e32 v141, 1.0, v141
	v_rcp_f32_e32 v141, v141
	s_nop 0
	v_mul_f32_e32 v0, v141, v0
	v_and_b32_e32 v141, 0xffff0000, v164
	v_mul_f32_e32 v145, 0xbfb8aa3b, v141
	v_exp_f32_e32 v145, v145
	v_mul_f32_e32 v0, v0, v174
	v_add_f32_e32 v145, 1.0, v145
	v_rcp_f32_e32 v145, v145
	s_nop 0
	v_mul_f32_e32 v141, v145, v141
	v_mul_f32_e32 v141, v141, v175
	v_cvt_pk_bf16_f32 v164, v0, v141
	v_lshlrev_b32_e32 v0, 16, v165
	v_mul_f32_e32 v141, 0xbfb8aa3b, v0
	v_exp_f32_e32 v141, v141
	s_nop 0
	v_add_f32_e32 v141, 1.0, v141
	v_rcp_f32_e32 v141, v141
	s_nop 0
	v_mul_f32_e32 v0, v141, v0
	v_and_b32_e32 v141, 0xffff0000, v165
	v_mul_f32_e32 v145, 0xbfb8aa3b, v141
	v_exp_f32_e32 v145, v145
	v_mul_f32_e32 v0, v0, v168
	v_add_f32_e32 v145, 1.0, v145
	v_rcp_f32_e32 v145, v145
	s_nop 0
	v_mul_f32_e32 v141, v145, v141
	v_mul_f32_e32 v141, v141, v169
	v_cvt_pk_bf16_f32 v165, v0, v141
	v_mov_b32_e32 v0, v167
	v_mad_u64_u32 v[162:163], s[14:15], v163, s4, v[0:1]
	s_waitcnt vmcnt(2)
	v_lshlrev_b32_e32 v0, 16, v160
	v_mul_f32_e32 v141, 0xbfb8aa3b, v0
	v_exp_f32_e32 v141, v141
	v_mov_b32_e32 v167, v162
	v_lshl_add_u64 v[162:163], v[166:167], 0, v[170:171]
	global_store_dwordx2 v[162:163], v[164:165], off
	v_add_f32_e32 v141, 1.0, v141
	v_rcp_f32_e32 v141, v141
	v_pk_add_f32 v[164:165], v[54:55], v[74:75]
	v_pk_add_f32 v[162:163], v[56:57], v[76:77]
	v_mul_f32_e32 v0, v141, v0
	v_and_b32_e32 v141, 0xffff0000, v160
	v_mul_f32_e32 v145, 0xbfb8aa3b, v141
	v_exp_f32_e32 v145, v145
	v_mul_f32_e32 v0, v0, v164
	v_add_f32_e32 v145, 1.0, v145
	v_rcp_f32_e32 v145, v145
	s_nop 0
	v_mul_f32_e32 v141, v145, v141
	v_mul_f32_e32 v141, v141, v165
	v_cvt_pk_bf16_f32 v160, v0, v141
	v_lshlrev_b32_e32 v0, 16, v161
	v_mul_f32_e32 v141, 0xbfb8aa3b, v0
	v_exp_f32_e32 v141, v141
	v_pk_add_f32 v[164:165], v[58:59], v[70:71]
	v_add_f32_e32 v141, 1.0, v141
	v_rcp_f32_e32 v141, v141
	s_nop 0
	v_mul_f32_e32 v0, v141, v0
	v_and_b32_e32 v141, 0xffff0000, v161
	v_mul_f32_e32 v145, 0xbfb8aa3b, v141
	v_exp_f32_e32 v145, v145
	v_mul_f32_e32 v0, v0, v162
	v_add_f32_e32 v145, 1.0, v145
	v_rcp_f32_e32 v145, v145
	s_nop 0
	v_mul_f32_e32 v141, v145, v141
	v_mul_f32_e32 v141, v141, v163
	v_cvt_pk_bf16_f32 v161, v0, v141
	s_waitcnt vmcnt(1)
	v_lshlrev_b32_e32 v0, 16, v158
	v_mul_f32_e32 v141, 0xbfb8aa3b, v0
	v_exp_f32_e32 v141, v141
	v_lshl_add_u64 v[162:163], v[166:167], 0, v[172:173]
	global_store_dwordx2 v[162:163], v[160:161], off offset:32
	v_pk_add_f32 v[160:161], v[60:61], v[72:73]
	v_add_f32_e32 v141, 1.0, v141
	v_rcp_f32_e32 v141, v141
	s_nop 0
	v_mul_f32_e32 v0, v141, v0
	v_and_b32_e32 v141, 0xffff0000, v158
	v_mul_f32_e32 v145, 0xbfb8aa3b, v141
	v_exp_f32_e32 v145, v145
	v_mul_f32_e32 v0, v0, v164
	v_add_f32_e32 v145, 1.0, v145
	v_rcp_f32_e32 v145, v145
	s_nop 0
	v_mul_f32_e32 v141, v145, v141
	v_mul_f32_e32 v141, v141, v165
	v_cvt_pk_bf16_f32 v158, v0, v141
	v_lshlrev_b32_e32 v0, 16, v159
	v_mul_f32_e32 v141, 0xbfb8aa3b, v0
	v_exp_f32_e32 v141, v141
	s_nop 0
	v_add_f32_e32 v141, 1.0, v141
	v_rcp_f32_e32 v141, v141
	s_nop 0
	v_mul_f32_e32 v0, v141, v0
	v_and_b32_e32 v141, 0xffff0000, v159
	v_mul_f32_e32 v145, 0xbfb8aa3b, v141
	v_exp_f32_e32 v145, v145
	v_mul_f32_e32 v0, v0, v160
	v_add_f32_e32 v145, 1.0, v145
	v_rcp_f32_e32 v145, v145
	s_nop 0
	v_mul_f32_e32 v141, v145, v141
	v_mul_f32_e32 v141, v141, v161
	v_cvt_pk_bf16_f32 v159, v0, v141
	s_waitcnt vmcnt(0)
	v_lshlrev_b32_e32 v0, 16, v156
	v_mul_f32_e32 v141, 0xbfb8aa3b, v0
	v_exp_f32_e32 v141, v141
	v_pk_add_f32 v[160:161], v[62:63], v[66:67]
	global_store_dwordx2 v[162:163], v[158:159], off offset:64
	v_pk_add_f32 v[158:159], v[64:65], v[68:69]
	v_add_f32_e32 v141, 1.0, v141
	v_rcp_f32_e32 v141, v141
	s_nop 0
	v_mul_f32_e32 v0, v141, v0
	v_and_b32_e32 v141, 0xffff0000, v156
	v_mul_f32_e32 v145, 0xbfb8aa3b, v141
	v_exp_f32_e32 v145, v145
	v_mul_f32_e32 v0, v0, v160
	v_add_f32_e32 v145, 1.0, v145
	v_rcp_f32_e32 v145, v145
	s_nop 0
	v_mul_f32_e32 v141, v145, v141
	v_mul_f32_e32 v141, v141, v161
	v_cvt_pk_bf16_f32 v156, v0, v141
	v_lshlrev_b32_e32 v0, 16, v157
	v_mul_f32_e32 v141, 0xbfb8aa3b, v0
	v_exp_f32_e32 v141, v141
	s_nop 0
	v_add_f32_e32 v141, 1.0, v141
	v_rcp_f32_e32 v141, v141
	s_nop 0
	v_mul_f32_e32 v0, v141, v0
	v_and_b32_e32 v141, 0xffff0000, v157
	v_mul_f32_e32 v145, 0xbfb8aa3b, v141
	v_exp_f32_e32 v145, v145
	v_mul_f32_e32 v0, v0, v158
	v_add_f32_e32 v145, 1.0, v145
	v_rcp_f32_e32 v145, v145
	s_nop 0
	v_mul_f32_e32 v141, v145, v141
	v_mul_f32_e32 v141, v141, v159
	v_cvt_pk_bf16_f32 v157, v0, v141
	global_store_dwordx2 v[162:163], v[156:157], off offset:96
	v_mul_lo_u32 v0, v248, s23
	v_or_b32_e32 v141, s11, v247
	v_sub_u32_e32 v0, v0, v141
	v_and_b32_e32 v141, 0xfff, v0
	v_or_b32_e32 v141, s40, v141
	v_mad_u64_u32 v[156:157], s[14:15], v141, s90, v[152:153]
	v_mad_i32_i24 v157, s41, v220, v157
	v_lshl_add_u64 v[156:157], v[156:157], 0, s[6:7]
	v_lshl_add_u64 v[156:157], v[156:157], 0, v[154:155]
	v_add_u32_e32 v141, 0xff0, v0
	v_lshl_add_u64 v[158:159], v[156:157], 0, s[94:95]
	v_add_co_u32_e32 v156, vcc, s10, v156
	v_and_b32_e32 v141, 0xfff, v141
	s_nop 0
	v_addc_co_u32_e32 v157, vcc, 0, v157, vcc
	v_or_b32_e32 v141, s40, v141
	global_load_dwordx2 v[182:183], v[156:157], off offset:1024
	global_load_dwordx2 v[180:181], v[158:159], off offset:32
	global_load_dwordx2 v[178:179], v[158:159], off offset:64
	global_load_dwordx2 v[176:177], v[158:159], off offset:96
	v_mad_u64_u32 v[156:157], s[14:15], v141, s90, v[152:153]
	v_mad_i32_i24 v157, s41, v220, v157
	v_lshl_add_u64 v[156:157], v[156:157], 0, s[6:7]
	v_lshl_add_u64 v[156:157], v[156:157], 0, v[154:155]
	v_add_u32_e32 v141, 0xfe0, v0
	v_lshl_add_u64 v[158:159], v[156:157], 0, s[94:95]
	v_add_co_u32_e32 v156, vcc, s10, v156
	v_and_b32_e32 v141, 0xfff, v141
	s_nop 0
	v_addc_co_u32_e32 v157, vcc, 0, v157, vcc
	v_or_b32_e32 v141, s40, v141
	v_add_u32_e32 v0, 0xfd0, v0
	global_load_dwordx2 v[174:175], v[156:157], off offset:1024
	global_load_dwordx2 v[172:173], v[158:159], off offset:32
	global_load_dwordx2 v[170:171], v[158:159], off offset:64
	global_load_dwordx2 v[168:169], v[158:159], off offset:96
	v_mad_u64_u32 v[156:157], s[14:15], v141, s90, v[152:153]
	v_and_b32_e32 v0, 0xfff, v0
	v_mad_i32_i24 v157, s41, v220, v157
	v_or_b32_e32 v0, s40, v0
	v_lshl_add_u64 v[156:157], v[156:157], 0, s[6:7]
	v_mad_u64_u32 v[152:153], s[14:15], v0, s90, v[152:153]
	v_lshl_add_u64 v[156:157], v[156:157], 0, v[154:155]
	v_mad_i32_i24 v153, s41, v220, v153
	v_lshl_add_u64 v[158:159], v[156:157], 0, s[94:95]
	v_add_co_u32_e32 v156, vcc, s10, v156
	v_lshl_add_u64 v[152:153], v[152:153], 0, s[6:7]
	s_nop 0
	v_addc_co_u32_e32 v157, vcc, 0, v157, vcc
	v_lshl_add_u64 v[152:153], v[152:153], 0, v[154:155]
	v_lshl_add_u64 v[184:185], v[152:153], 0, s[94:95]
	v_add_co_u32_e32 v152, vcc, 0x114ed000, v152
	global_load_dwordx2 v[166:167], v[156:157], off offset:1024
	global_load_dwordx2 v[164:165], v[158:159], off offset:32
	global_load_dwordx2 v[162:163], v[158:159], off offset:64
	global_load_dwordx2 v[160:161], v[158:159], off offset:96
	v_addc_co_u32_e32 v153, vcc, 0, v153, vcc
	global_load_dwordx2 v[158:159], v[152:153], off offset:1024
	global_load_dwordx2 v[156:157], v[184:185], off offset:32
	global_load_dwordx2 v[154:155], v[184:185], off offset:64
	s_nop 0
	global_load_dwordx2 v[152:153], v[184:185], off offset:96
	v_add_u32_e32 v0, s11, v148
	v_cmp_lt_i32_e32 vcc, 0, v0
	s_and_saveexec_b64 s[6:7], vcc
	s_cbranch_execz .LBB0_870
	s_waitcnt vmcnt(15)
	v_lshlrev_b32_e32 v184, 16, v182
	v_sub_u32_e32 v148, 0x1000, v0
	v_mul_f32_e32 v0, 0xbfb8aa3b, v184
	v_exp_f32_e32 v0, v0
	v_and_b32_e32 v185, 0xffff0000, v182
	v_lshlrev_b32_e32 v182, 16, v183
	v_sub_f32_e32 v127, v3, v127
	v_add_f32_e32 v0, 1.0, v0
	v_rcp_f32_e32 v186, v0
	v_mul_f32_e32 v0, 0xbfb8aa3b, v185
	v_exp_f32_e32 v0, v0
	v_sub_f32_e32 v126, v2, v126
	v_and_b32_e32 v183, 0xffff0000, v183
	v_sub_f32_e32 v129, v5, v129
	v_add_f32_e32 v0, 1.0, v0
	v_rcp_f32_e32 v187, v0
	v_mul_f32_e32 v0, 0xbfb8aa3b, v182
	v_exp_f32_e32 v0, v0
	v_sub_f32_e32 v128, v4, v128
	v_pk_mul_f32 v[184:185], v[186:187], v[184:185]
	v_ashrrev_i32_e32 v149, 31, v148
	v_add_f32_e32 v0, 1.0, v0
	v_pk_mul_f32 v[126:127], v[184:185], v[126:127]
	v_rcp_f32_e32 v184, v0
	v_mul_f32_e32 v0, 0xbfb8aa3b, v183
	v_exp_f32_e32 v0, v0
	v_lshl_add_u64 v[148:149], s[40:41], 0, v[148:149]
	v_cvt_pk_bf16_f32 v126, v126, v127
	v_sub_f32_e32 v123, v7, v123
	v_add_f32_e32 v0, 1.0, v0
	v_rcp_f32_e32 v185, v0
	v_sub_f32_e32 v122, v6, v122
	v_sub_f32_e32 v125, v9, v125
	v_sub_f32_e32 v124, v8, v124
	v_pk_mul_f32 v[182:183], v[184:185], v[182:183]
	v_sub_f32_e32 v119, v11, v119
	v_pk_mul_f32 v[128:129], v[182:183], v[128:129]
	v_sub_f32_e32 v118, v10, v118
	v_cvt_pk_bf16_f32 v127, v128, v129
	v_mov_b64_e32 v[128:129], s[88:89]
	v_mad_u64_u32 v[128:129], s[14:15], v148, s4, v[128:129]
	v_mad_i32_i24 v129, v149, s4, v129
	v_lshl_add_u64 v[148:149], v[138:139], 1, v[128:129]
	global_store_dwordx2 v[148:149], v[126:127], off
	s_waitcnt vmcnt(15)
	v_lshlrev_b32_e32 v126, 16, v180
	v_mul_f32_e32 v0, 0xbfb8aa3b, v126
	v_exp_f32_e32 v0, v0
	v_and_b32_e32 v127, 0xffff0000, v180
	v_sub_f32_e32 v121, v13, v121
	v_sub_f32_e32 v120, v12, v120
	v_add_f32_e32 v0, 1.0, v0
	v_rcp_f32_e32 v148, v0
	v_mul_f32_e32 v0, 0xbfb8aa3b, v127
	v_exp_f32_e32 v0, v0
	v_sub_f32_e32 v115, v15, v115
	v_sub_f32_e32 v114, v14, v114
	v_sub_f32_e32 v117, v17, v117
	v_add_f32_e32 v0, 1.0, v0
	v_rcp_f32_e32 v149, v0
	v_sub_f32_e32 v116, v16, v116
	v_pk_mul_f32 v[126:127], v[148:149], v[126:127]
	s_nop 0
	v_pk_mul_f32 v[122:123], v[126:127], v[122:123]
	v_lshlrev_b32_e32 v126, 16, v181
	v_mul_f32_e32 v0, 0xbfb8aa3b, v126
	v_exp_f32_e32 v0, v0
	v_and_b32_e32 v127, 0xffff0000, v181
	v_cvt_pk_bf16_f32 v122, v122, v123
	v_add_f32_e32 v0, 1.0, v0
	v_rcp_f32_e32 v148, v0
	v_mul_f32_e32 v0, 0xbfb8aa3b, v127
	v_exp_f32_e32 v0, v0
	s_nop 0
	v_add_f32_e32 v0, 1.0, v0
	v_rcp_f32_e32 v149, v0
	s_nop 0
	v_pk_mul_f32 v[126:127], v[148:149], v[126:127]
	s_nop 0
	v_pk_mul_f32 v[124:125], v[126:127], v[124:125]
	s_nop 0
	v_cvt_pk_bf16_f32 v123, v124, v125
	v_lshl_add_u64 v[124:125], v[142:143], 1, v[128:129]
	global_store_dwordx2 v[124:125], v[122:123], off offset:32
	s_waitcnt vmcnt(15)
	v_lshlrev_b32_e32 v122, 16, v178
	v_mul_f32_e32 v0, 0xbfb8aa3b, v122
	v_exp_f32_e32 v0, v0
	v_and_b32_e32 v123, 0xffff0000, v178
	v_add_f32_e32 v0, 1.0, v0
	v_rcp_f32_e32 v126, v0
	v_mul_f32_e32 v0, 0xbfb8aa3b, v123
	v_exp_f32_e32 v0, v0
	s_nop 0
	v_add_f32_e32 v0, 1.0, v0
	v_rcp_f32_e32 v127, v0
	s_nop 0
	v_pk_mul_f32 v[122:123], v[126:127], v[122:123]
	s_nop 0
	v_pk_mul_f32 v[118:119], v[122:123], v[118:119]
	v_lshlrev_b32_e32 v122, 16, v179
	v_mul_f32_e32 v0, 0xbfb8aa3b, v122
	v_exp_f32_e32 v0, v0
	v_and_b32_e32 v123, 0xffff0000, v179
	v_cvt_pk_bf16_f32 v118, v118, v119
	v_add_f32_e32 v0, 1.0, v0
	v_rcp_f32_e32 v126, v0
	v_mul_f32_e32 v0, 0xbfb8aa3b, v123
	v_exp_f32_e32 v0, v0
	s_nop 0
	v_add_f32_e32 v0, 1.0, v0
	v_rcp_f32_e32 v127, v0
	s_nop 0
	v_pk_mul_f32 v[122:123], v[126:127], v[122:123]
	s_nop 0
	v_pk_mul_f32 v[120:121], v[122:123], v[120:121]
	s_nop 0
	v_cvt_pk_bf16_f32 v119, v120, v121
	global_store_dwordx2 v[124:125], v[118:119], off offset:64
	s_waitcnt vmcnt(15)
	v_lshlrev_b32_e32 v118, 16, v176
	v_mul_f32_e32 v0, 0xbfb8aa3b, v118
	v_exp_f32_e32 v0, v0
	v_and_b32_e32 v119, 0xffff0000, v176
	v_add_f32_e32 v0, 1.0, v0
	v_rcp_f32_e32 v120, v0
	v_mul_f32_e32 v0, 0xbfb8aa3b, v119
	v_exp_f32_e32 v0, v0
	s_nop 0
	v_add_f32_e32 v0, 1.0, v0
	v_rcp_f32_e32 v121, v0
	s_nop 0
	v_pk_mul_f32 v[118:119], v[120:121], v[118:119]
	s_nop 0
	v_pk_mul_f32 v[114:115], v[118:119], v[114:115]
	v_lshlrev_b32_e32 v118, 16, v177
	v_mul_f32_e32 v0, 0xbfb8aa3b, v118
	v_exp_f32_e32 v0, v0
	v_and_b32_e32 v119, 0xffff0000, v177
	v_cvt_pk_bf16_f32 v114, v114, v115
	v_add_f32_e32 v0, 1.0, v0
	v_rcp_f32_e32 v120, v0
	v_mul_f32_e32 v0, 0xbfb8aa3b, v119
	v_exp_f32_e32 v0, v0
	s_nop 0
	v_add_f32_e32 v0, 1.0, v0
	v_rcp_f32_e32 v121, v0
	s_nop 0
	v_pk_mul_f32 v[118:119], v[120:121], v[118:119]
	s_nop 0
	v_pk_mul_f32 v[116:117], v[118:119], v[116:117]
	s_nop 0
	v_cvt_pk_bf16_f32 v115, v116, v117
	global_store_dwordx2 v[124:125], v[114:115], off offset:96
